# v63 + bf16 K-loops: the k0/k1 MFMAs of each accumulator issued back to back (accumulate chain), like the int8 loops
# baseline (speedup 1.0000x reference)
.LBB0_412:
	ds_read_b128 v[130:133], v191
	ds_read_b128 v[134:137], v191 offset:1024
	ds_read_b128 v[138:141], v191 offset:2048
	ds_read_b128 v[142:145], v191 offset:3072
	ds_read_b128 v[146:149], v192
	ds_read_b128 v[150:153], v192 offset:1024
	ds_read_b128 v[174:177], v192 offset:2048
	s_waitcnt lgkmcnt(0)
	ds_read_b128 v[178:181], v192 offset:3072
	s_add_u32 s42, s40, 0xfff00080
	s_addc_u32 s43, s41, -1
	s_cmp_eq_u32 s29, 60
	s_cselect_b32 s45, s0, s43
	s_cselect_b32 s44, s1, s42
	s_cselect_b32 s43, s7, s27
	s_cselect_b32 s42, s14, s15
	v_lshl_add_u64 v[186:187], s[40:41], 0, v[170:171]
	s_add_i32 m0, s9, 0xc000
	ds_read_b128 v[182:185], v193
	ds_read_b128 v[204:207], v193 offset:1024
	ds_read_b128 v[208:211], v193 offset:2048
	ds_read_b128 v[212:215], v193 offset:3072
	ds_read_b128 v[216:219], v193 offset:4096
	ds_read_b128 v[220:223], v193 offset:5120
	ds_read_b128 v[224:227], v193 offset:6144
	ds_read_b128 v[234:237], v193 offset:7168
	global_load_lds_dwordx4 v[186:187], off
	v_lshl_add_u64 v[186:187], s[40:41], 0, v[172:173]
	s_add_i32 m0, s9, 0xe000
	s_nop 0
	global_load_lds_dwordx4 v[186:187], off
	s_waitcnt vmcnt(8)
	s_waitcnt lgkmcnt(0)
	s_barrier
	s_waitcnt lgkmcnt(0)
	v_mfma_f32_16x16x32_bf16 v[126:129], v[130:133], v[182:185], v[126:129]
	v_mfma_f32_16x16x32_bf16 v[126:129], v[134:137], v[204:207], v[126:129]
	v_mfma_f32_16x16x32_bf16 v[122:125], v[138:141], v[182:185], v[122:125]
	v_mfma_f32_16x16x32_bf16 v[122:125], v[142:145], v[204:207], v[122:125]
	v_mfma_f32_16x16x32_bf16 v[118:121], v[130:133], v[208:211], v[118:121]
	v_mfma_f32_16x16x32_bf16 v[118:121], v[134:137], v[212:215], v[118:121]
	v_mfma_f32_16x16x32_bf16 v[110:113], v[138:141], v[208:211], v[110:113]
	v_mfma_f32_16x16x32_bf16 v[110:113], v[142:145], v[212:215], v[110:113]
	v_mfma_f32_16x16x32_bf16 v[102:105], v[130:133], v[216:219], v[102:105]
	v_mfma_f32_16x16x32_bf16 v[102:105], v[134:137], v[220:223], v[102:105]
	v_mfma_f32_16x16x32_bf16 v[94:97], v[138:141], v[216:219], v[94:97]
	v_mfma_f32_16x16x32_bf16 v[94:97], v[142:145], v[220:223], v[94:97]
	v_mfma_f32_16x16x32_bf16 v[86:89], v[130:133], v[224:227], v[86:89]
	v_mfma_f32_16x16x32_bf16 v[86:89], v[134:137], v[234:237], v[86:89]
	v_mfma_f32_16x16x32_bf16 v[78:81], v[138:141], v[224:227], v[78:81]
	v_mfma_f32_16x16x32_bf16 v[78:81], v[142:145], v[234:237], v[78:81]
	v_mfma_f32_16x16x32_bf16 v[114:117], v[146:149], v[182:185], v[114:117]
	v_mfma_f32_16x16x32_bf16 v[114:117], v[150:153], v[204:207], v[114:117]
	v_mfma_f32_16x16x32_bf16 v[106:109], v[174:177], v[182:185], v[106:109]
	v_mfma_f32_16x16x32_bf16 v[106:109], v[178:181], v[204:207], v[106:109]
	v_mfma_f32_16x16x32_bf16 v[98:101], v[146:149], v[208:211], v[98:101]
	v_mfma_f32_16x16x32_bf16 v[98:101], v[150:153], v[212:215], v[98:101]
	v_mfma_f32_16x16x32_bf16 v[90:93], v[174:177], v[208:211], v[90:93]
	v_mfma_f32_16x16x32_bf16 v[90:93], v[178:181], v[212:215], v[90:93]
	v_mfma_f32_16x16x32_bf16 v[82:85], v[146:149], v[216:219], v[82:85]
	v_mfma_f32_16x16x32_bf16 v[82:85], v[150:153], v[220:223], v[82:85]
	v_mfma_f32_16x16x32_bf16 v[74:77], v[174:177], v[216:219], v[74:77]
	v_mfma_f32_16x16x32_bf16 v[74:77], v[178:181], v[220:223], v[74:77]
	v_mfma_f32_16x16x32_bf16 v[70:73], v[146:149], v[224:227], v[70:73]
	v_mfma_f32_16x16x32_bf16 v[70:73], v[150:153], v[234:237], v[70:73]
	v_mfma_f32_16x16x32_bf16 v[66:69], v[174:177], v[224:227], v[66:69]
	v_mfma_f32_16x16x32_bf16 v[66:69], v[178:181], v[234:237], v[66:69]
	s_barrier
	s_add_i32 s46, s52, s8
	v_lshl_add_u64 v[186:187], s[42:43], 0, v[158:159]
	s_mov_b32 m0, s46
	ds_read_b128 v[182:185], v193 offset:16384
	ds_read_b128 v[204:207], v193 offset:17408
	ds_read_b128 v[208:211], v193 offset:18432
	ds_read_b128 v[212:215], v193 offset:19456
	ds_read_b128 v[216:219], v193 offset:20480
	ds_read_b128 v[220:223], v193 offset:21504
	ds_read_b128 v[224:227], v193 offset:22528
	ds_read_b128 v[234:237], v193 offset:23552
	global_load_lds_dwordx4 v[186:187], off
	s_add_i32 m0, s46, 0x2000
	s_add_u32 s46, s42, 0x100000
	v_lshl_add_u64 v[194:195], s[42:43], 0, v[162:163]
	s_addc_u32 s47, s43, 0
	s_add_i32 s56, s53, s8
	global_load_lds_dwordx4 v[194:195], off
	v_lshl_add_u64 v[200:201], s[46:47], 0, v[158:159]
	s_mov_b32 m0, s56
	v_lshl_add_u64 v[238:239], s[44:45], 0, v[160:161]
	global_load_lds_dwordx4 v[200:201], off
	v_lshl_add_u64 v[200:201], s[46:47], 0, v[162:163]
	s_add_i32 m0, s56, 0x2000
	s_nop 0
	global_load_lds_dwordx4 v[200:201], off
	v_lshl_add_u64 v[200:201], s[44:45], 0, v[156:157]
	s_mov_b32 m0, s9
	s_nop 0
	global_load_lds_dwordx4 v[200:201], off
	s_mov_b32 m0, s13
	s_nop 0
	global_load_lds_dwordx4 v[238:239], off
	s_waitcnt vmcnt(8)
	s_waitcnt lgkmcnt(0)
	s_barrier
	s_waitcnt lgkmcnt(0)
	v_mfma_f32_16x16x32_bf16 v[62:65], v[130:133], v[182:185], v[62:65]
	v_mfma_f32_16x16x32_bf16 v[62:65], v[134:137], v[204:207], v[62:65]
	v_mfma_f32_16x16x32_bf16 v[58:61], v[138:141], v[182:185], v[58:61]
	v_mfma_f32_16x16x32_bf16 v[58:61], v[142:145], v[204:207], v[58:61]
	v_mfma_f32_16x16x32_bf16 v[54:57], v[130:133], v[208:211], v[54:57]
	v_mfma_f32_16x16x32_bf16 v[54:57], v[134:137], v[212:215], v[54:57]
	v_mfma_f32_16x16x32_bf16 v[46:49], v[138:141], v[208:211], v[46:49]
	v_mfma_f32_16x16x32_bf16 v[46:49], v[142:145], v[212:215], v[46:49]
	v_mfma_f32_16x16x32_bf16 v[38:41], v[130:133], v[216:219], v[38:41]
	v_mfma_f32_16x16x32_bf16 v[38:41], v[134:137], v[220:223], v[38:41]
	v_mfma_f32_16x16x32_bf16 v[30:33], v[138:141], v[216:219], v[30:33]
	v_mfma_f32_16x16x32_bf16 v[30:33], v[142:145], v[220:223], v[30:33]
	v_mfma_f32_16x16x32_bf16 v[22:25], v[130:133], v[224:227], v[22:25]
	v_mfma_f32_16x16x32_bf16 v[22:25], v[134:137], v[234:237], v[22:25]
	v_mfma_f32_16x16x32_bf16 v[14:17], v[138:141], v[224:227], v[14:17]
	v_mfma_f32_16x16x32_bf16 v[14:17], v[142:145], v[234:237], v[14:17]
	v_mfma_f32_16x16x32_bf16 v[50:53], v[146:149], v[182:185], v[50:53]
	v_mfma_f32_16x16x32_bf16 v[50:53], v[150:153], v[204:207], v[50:53]
	v_mfma_f32_16x16x32_bf16 v[42:45], v[174:177], v[182:185], v[42:45]
	v_mfma_f32_16x16x32_bf16 v[42:45], v[178:181], v[204:207], v[42:45]
	v_mfma_f32_16x16x32_bf16 v[34:37], v[146:149], v[208:211], v[34:37]
	v_mfma_f32_16x16x32_bf16 v[34:37], v[150:153], v[212:215], v[34:37]
	v_mfma_f32_16x16x32_bf16 v[26:29], v[174:177], v[208:211], v[26:29]
	v_mfma_f32_16x16x32_bf16 v[26:29], v[178:181], v[212:215], v[26:29]
	v_mfma_f32_16x16x32_bf16 v[18:21], v[146:149], v[216:219], v[18:21]
	v_mfma_f32_16x16x32_bf16 v[18:21], v[150:153], v[220:223], v[18:21]
	v_mfma_f32_16x16x32_bf16 v[10:13], v[174:177], v[216:219], v[10:13]
	v_mfma_f32_16x16x32_bf16 v[10:13], v[178:181], v[220:223], v[10:13]
	v_mfma_f32_16x16x32_bf16 v[6:9], v[146:149], v[224:227], v[6:9]
	v_mfma_f32_16x16x32_bf16 v[6:9], v[150:153], v[234:237], v[6:9]
	v_mfma_f32_16x16x32_bf16 v[2:5], v[174:177], v[224:227], v[2:5]
	v_mfma_f32_16x16x32_bf16 v[2:5], v[178:181], v[234:237], v[2:5]
	s_barrier
	s_add_i32 s46, 0, 0x18000
	s_add_i32 s47, 0, 0x1c000
	v_add_u32_e32 v142, s46, v188
	v_add_u32_e32 v164, s47, v188
	ds_read_b128 v[130:133], v142
	ds_read_b128 v[134:137], v142 offset:1024
	ds_read_b128 v[138:141], v142 offset:2048
	ds_read_b128 v[142:145], v142 offset:3072
	ds_read_b128 v[146:149], v164
	ds_read_b128 v[150:153], v164 offset:1024
	ds_read_b128 v[174:177], v164 offset:2048
	ds_read_b128 v[178:181], v164 offset:3072
	s_add_u32 s44, s44, 0x100000
	s_addc_u32 s45, s45, 0
	s_mov_b32 m0, s33
	v_lshl_add_u64 v[240:241], s[44:45], 0, v[156:157]
	ds_read_b128 v[182:185], v193 offset:32768
	ds_read_b128 v[204:207], v193 offset:33792
	ds_read_b128 v[208:211], v193 offset:34816
	ds_read_b128 v[212:215], v193 offset:35840
	ds_read_b128 v[216:219], v193 offset:36864
	ds_read_b128 v[220:223], v193 offset:37888
	ds_read_b128 v[224:227], v193 offset:38912
	ds_read_b128 v[234:237], v193 offset:39936
	global_load_lds_dwordx4 v[240:241], off
	v_lshl_add_u64 v[240:241], s[44:45], 0, v[160:161]
	s_mov_b32 m0, s39
	s_nop 0
	global_load_lds_dwordx4 v[240:241], off
	s_waitcnt vmcnt(8)
	s_waitcnt lgkmcnt(0)
	s_barrier
	s_waitcnt lgkmcnt(0)
	v_mfma_f32_16x16x32_bf16 v[126:129], v[130:133], v[182:185], v[126:129]
	v_mfma_f32_16x16x32_bf16 v[126:129], v[134:137], v[204:207], v[126:129]
	v_mfma_f32_16x16x32_bf16 v[122:125], v[138:141], v[182:185], v[122:125]
	v_mfma_f32_16x16x32_bf16 v[122:125], v[142:145], v[204:207], v[122:125]
	v_mfma_f32_16x16x32_bf16 v[118:121], v[130:133], v[208:211], v[118:121]
	v_mfma_f32_16x16x32_bf16 v[118:121], v[134:137], v[212:215], v[118:121]
	v_mfma_f32_16x16x32_bf16 v[110:113], v[138:141], v[208:211], v[110:113]
	v_mfma_f32_16x16x32_bf16 v[110:113], v[142:145], v[212:215], v[110:113]
	v_mfma_f32_16x16x32_bf16 v[102:105], v[130:133], v[216:219], v[102:105]
	v_mfma_f32_16x16x32_bf16 v[102:105], v[134:137], v[220:223], v[102:105]
	v_mfma_f32_16x16x32_bf16 v[94:97], v[138:141], v[216:219], v[94:97]
	v_mfma_f32_16x16x32_bf16 v[94:97], v[142:145], v[220:223], v[94:97]
	v_mfma_f32_16x16x32_bf16 v[86:89], v[130:133], v[224:227], v[86:89]
	v_mfma_f32_16x16x32_bf16 v[86:89], v[134:137], v[234:237], v[86:89]
	v_mfma_f32_16x16x32_bf16 v[78:81], v[138:141], v[224:227], v[78:81]
	v_mfma_f32_16x16x32_bf16 v[78:81], v[142:145], v[234:237], v[78:81]
	v_mfma_f32_16x16x32_bf16 v[114:117], v[146:149], v[182:185], v[114:117]
	v_mfma_f32_16x16x32_bf16 v[114:117], v[150:153], v[204:207], v[114:117]
	v_mfma_f32_16x16x32_bf16 v[106:109], v[174:177], v[182:185], v[106:109]
	v_mfma_f32_16x16x32_bf16 v[106:109], v[178:181], v[204:207], v[106:109]
	v_mfma_f32_16x16x32_bf16 v[98:101], v[146:149], v[208:211], v[98:101]
	v_mfma_f32_16x16x32_bf16 v[98:101], v[150:153], v[212:215], v[98:101]
	v_mfma_f32_16x16x32_bf16 v[90:93], v[174:177], v[208:211], v[90:93]
	v_mfma_f32_16x16x32_bf16 v[90:93], v[178:181], v[212:215], v[90:93]
	v_mfma_f32_16x16x32_bf16 v[82:85], v[146:149], v[216:219], v[82:85]
	v_mfma_f32_16x16x32_bf16 v[82:85], v[150:153], v[220:223], v[82:85]
	v_mfma_f32_16x16x32_bf16 v[74:77], v[174:177], v[216:219], v[74:77]
	v_mfma_f32_16x16x32_bf16 v[74:77], v[178:181], v[220:223], v[74:77]
	v_mfma_f32_16x16x32_bf16 v[70:73], v[146:149], v[224:227], v[70:73]
	v_mfma_f32_16x16x32_bf16 v[70:73], v[150:153], v[234:237], v[70:73]
	v_mfma_f32_16x16x32_bf16 v[66:69], v[174:177], v[224:227], v[66:69]
	v_mfma_f32_16x16x32_bf16 v[66:69], v[178:181], v[234:237], v[66:69]
	s_barrier
	s_add_i32 s44, s46, s8
	v_lshl_add_u64 v[186:187], v[186:187], 0, s[20:21]
	s_mov_b32 m0, s44
	ds_read_b128 v[182:185], v193 offset:49152
	ds_read_b128 v[204:207], v193 offset:50176
	ds_read_b128 v[208:211], v193 offset:51200
	ds_read_b128 v[212:215], v193 offset:52224
	ds_read_b128 v[216:219], v193 offset:53248
	ds_read_b128 v[220:223], v193 offset:54272
	ds_read_b128 v[224:227], v193 offset:55296
	ds_read_b128 v[234:237], v193 offset:56320
	global_load_lds_dwordx4 v[186:187], off
	s_add_i32 m0, s44, 0x2000
	s_add_u32 s42, s42, 0x100080
	v_lshl_add_u64 v[186:187], v[194:195], 0, s[20:21]
	s_addc_u32 s43, s43, 0
	s_add_i32 s44, s47, s8
	global_load_lds_dwordx4 v[186:187], off
	v_lshl_add_u64 v[186:187], s[42:43], 0, v[158:159]
	s_mov_b32 m0, s44
	s_nop 0
	global_load_lds_dwordx4 v[186:187], off
	v_lshl_add_u64 v[186:187], s[42:43], 0, v[162:163]
	s_add_i32 m0, s44, 0x2000
	s_nop 0
	global_load_lds_dwordx4 v[186:187], off
	v_lshl_add_u64 v[186:187], v[200:201], 0, s[20:21]
	s_mov_b32 m0, s50
	s_nop 0
	global_load_lds_dwordx4 v[186:187], off
	v_lshl_add_u64 v[186:187], v[238:239], 0, s[20:21]
	s_mov_b32 m0, s51
	s_nop 0
	global_load_lds_dwordx4 v[186:187], off
	s_waitcnt vmcnt(8)
	s_waitcnt lgkmcnt(0)
	s_barrier
	s_waitcnt lgkmcnt(0)
	v_mfma_f32_16x16x32_bf16 v[62:65], v[130:133], v[182:185], v[62:65]
	v_mfma_f32_16x16x32_bf16 v[62:65], v[134:137], v[204:207], v[62:65]
	v_mfma_f32_16x16x32_bf16 v[58:61], v[138:141], v[182:185], v[58:61]
	v_mfma_f32_16x16x32_bf16 v[58:61], v[142:145], v[204:207], v[58:61]
	v_mfma_f32_16x16x32_bf16 v[54:57], v[130:133], v[208:211], v[54:57]
	v_mfma_f32_16x16x32_bf16 v[54:57], v[134:137], v[212:215], v[54:57]
	v_mfma_f32_16x16x32_bf16 v[46:49], v[138:141], v[208:211], v[46:49]
	v_mfma_f32_16x16x32_bf16 v[46:49], v[142:145], v[212:215], v[46:49]
	v_mfma_f32_16x16x32_bf16 v[38:41], v[130:133], v[216:219], v[38:41]
	v_mfma_f32_16x16x32_bf16 v[38:41], v[134:137], v[220:223], v[38:41]
	v_mfma_f32_16x16x32_bf16 v[30:33], v[138:141], v[216:219], v[30:33]
	v_mfma_f32_16x16x32_bf16 v[30:33], v[142:145], v[220:223], v[30:33]
	v_mfma_f32_16x16x32_bf16 v[22:25], v[130:133], v[224:227], v[22:25]
	v_mfma_f32_16x16x32_bf16 v[22:25], v[134:137], v[234:237], v[22:25]
	v_mfma_f32_16x16x32_bf16 v[14:17], v[138:141], v[224:227], v[14:17]
	v_mfma_f32_16x16x32_bf16 v[14:17], v[142:145], v[234:237], v[14:17]
	v_mfma_f32_16x16x32_bf16 v[50:53], v[146:149], v[182:185], v[50:53]
	v_mfma_f32_16x16x32_bf16 v[50:53], v[150:153], v[204:207], v[50:53]
	v_mfma_f32_16x16x32_bf16 v[42:45], v[174:177], v[182:185], v[42:45]
	v_mfma_f32_16x16x32_bf16 v[42:45], v[178:181], v[204:207], v[42:45]
	v_mfma_f32_16x16x32_bf16 v[34:37], v[146:149], v[208:211], v[34:37]
	v_mfma_f32_16x16x32_bf16 v[34:37], v[150:153], v[212:215], v[34:37]
	v_mfma_f32_16x16x32_bf16 v[26:29], v[174:177], v[208:211], v[26:29]
	v_mfma_f32_16x16x32_bf16 v[26:29], v[178:181], v[212:215], v[26:29]
	v_mfma_f32_16x16x32_bf16 v[18:21], v[146:149], v[216:219], v[18:21]
	v_mfma_f32_16x16x32_bf16 v[18:21], v[150:153], v[220:223], v[18:21]
	v_mfma_f32_16x16x32_bf16 v[10:13], v[174:177], v[216:219], v[10:13]
	v_mfma_f32_16x16x32_bf16 v[10:13], v[178:181], v[220:223], v[10:13]
	v_mfma_f32_16x16x32_bf16 v[6:9], v[146:149], v[224:227], v[6:9]
	v_mfma_f32_16x16x32_bf16 v[6:9], v[150:153], v[234:237], v[6:9]
	v_mfma_f32_16x16x32_bf16 v[2:5], v[174:177], v[224:227], v[2:5]
	v_mfma_f32_16x16x32_bf16 v[2:5], v[178:181], v[234:237], v[2:5]
	s_barrier
	s_add_i32 s29, s29, 2
	s_add_u32 s40, s40, 0x100
	s_addc_u32 s41, s41, 0
	s_add_u32 s15, s15, 0x100
	s_addc_u32 s27, s27, 0
	s_cmp_gt_u32 s29, 61
	s_cbranch_scc0 .LBB0_412
	s_and_b64 vcc, exec, s[22:23]
	s_cbranch_vccz .LBB0_415
	s_barrier

.LBB0_514:
	ds_read_b128 v[156:159], v146
	ds_read_b128 v[160:163], v146 offset:1024
	ds_read_b128 v[164:167], v146 offset:2048
	ds_read_b128 v[168:171], v146 offset:3072
	ds_read_b128 v[172:175], v147
	s_waitcnt lgkmcnt(0)
	ds_read_b128 v[176:179], v147 offset:1024
	ds_read_b128 v[180:183], v147 offset:2048
	ds_read_b128 v[184:187], v147 offset:3072
	s_add_u32 s28, s26, 0xfff00080
	s_addc_u32 s29, s27, -1
	s_cmp_eq_u32 s50, 4
	s_cselect_b32 s31, s19, s29
	s_cselect_b32 s30, s18, s28
	s_cselect_b32 s29, s21, s49
	s_cselect_b32 s28, s20, s23
	s_mov_b32 m0, s36
	v_lshl_add_u64 v[142:143], s[26:27], 0, v[138:139]
	ds_read_b128 v[190:193], v148
	ds_read_b128 v[204:207], v148 offset:1024
	ds_read_b128 v[208:211], v148 offset:2048
	ds_read_b128 v[212:215], v148 offset:3072
	ds_read_b128 v[216:219], v148 offset:4096
	ds_read_b128 v[220:223], v148 offset:5120
	ds_read_b128 v[224:227], v148 offset:6144
	ds_read_b128 v[234:237], v148 offset:7168
	global_load_lds_dwordx4 v[142:143], off
	v_lshl_add_u64 v[142:143], s[26:27], 0, v[140:141]
	s_mov_b32 m0, s37
	s_nop 0
	global_load_lds_dwordx4 v[142:143], off
	s_waitcnt vmcnt(8)
	s_waitcnt lgkmcnt(0)
	s_barrier
	s_waitcnt lgkmcnt(0)
	v_mfma_f32_16x16x32_bf16 v[126:129], v[156:159], v[190:193], v[126:129]
	v_mfma_f32_16x16x32_bf16 v[126:129], v[160:163], v[204:207], v[126:129]
	v_mfma_f32_16x16x32_bf16 v[122:125], v[164:167], v[190:193], v[122:125]
	v_mfma_f32_16x16x32_bf16 v[122:125], v[168:171], v[204:207], v[122:125]
	v_mfma_f32_16x16x32_bf16 v[118:121], v[156:159], v[208:211], v[118:121]
	v_mfma_f32_16x16x32_bf16 v[118:121], v[160:163], v[212:215], v[118:121]
	v_mfma_f32_16x16x32_bf16 v[110:113], v[164:167], v[208:211], v[110:113]
	v_mfma_f32_16x16x32_bf16 v[110:113], v[168:171], v[212:215], v[110:113]
	v_mfma_f32_16x16x32_bf16 v[102:105], v[156:159], v[216:219], v[102:105]
	v_mfma_f32_16x16x32_bf16 v[102:105], v[160:163], v[220:223], v[102:105]
	v_mfma_f32_16x16x32_bf16 v[94:97], v[164:167], v[216:219], v[94:97]
	v_mfma_f32_16x16x32_bf16 v[94:97], v[168:171], v[220:223], v[94:97]
	v_mfma_f32_16x16x32_bf16 v[82:85], v[156:159], v[224:227], v[82:85]
	v_mfma_f32_16x16x32_bf16 v[82:85], v[160:163], v[234:237], v[82:85]
	v_mfma_f32_16x16x32_bf16 v[74:77], v[164:167], v[224:227], v[74:77]
	v_mfma_f32_16x16x32_bf16 v[74:77], v[168:171], v[234:237], v[74:77]
	v_mfma_f32_16x16x32_bf16 v[114:117], v[172:175], v[190:193], v[114:117]
	v_mfma_f32_16x16x32_bf16 v[114:117], v[176:179], v[204:207], v[114:117]
	v_mfma_f32_16x16x32_bf16 v[106:109], v[180:183], v[190:193], v[106:109]
	v_mfma_f32_16x16x32_bf16 v[106:109], v[184:187], v[204:207], v[106:109]
	v_mfma_f32_16x16x32_bf16 v[98:101], v[172:175], v[208:211], v[98:101]
	v_mfma_f32_16x16x32_bf16 v[98:101], v[176:179], v[212:215], v[98:101]
	v_mfma_f32_16x16x32_bf16 v[90:93], v[180:183], v[208:211], v[90:93]
	v_mfma_f32_16x16x32_bf16 v[90:93], v[184:187], v[212:215], v[90:93]
	v_mfma_f32_16x16x32_bf16 v[86:89], v[172:175], v[216:219], v[86:89]
	v_mfma_f32_16x16x32_bf16 v[86:89], v[176:179], v[220:223], v[86:89]
	v_mfma_f32_16x16x32_bf16 v[78:81], v[180:183], v[216:219], v[78:81]
	v_mfma_f32_16x16x32_bf16 v[78:81], v[184:187], v[220:223], v[78:81]
	v_mfma_f32_16x16x32_bf16 v[70:73], v[172:175], v[224:227], v[70:73]
	v_mfma_f32_16x16x32_bf16 v[70:73], v[176:179], v[234:237], v[70:73]
	v_mfma_f32_16x16x32_bf16 v[66:69], v[180:183], v[224:227], v[66:69]
	v_mfma_f32_16x16x32_bf16 v[66:69], v[184:187], v[234:237], v[66:69]
	s_barrier
	s_mov_b32 m0, s38
	v_lshl_add_u64 v[142:143], s[28:29], 0, v[134:135]
	s_add_u32 s52, s28, 0x20000
	ds_read_b128 v[190:193], v148 offset:16384
	ds_read_b128 v[204:207], v148 offset:17408
	ds_read_b128 v[208:211], v148 offset:18432
	ds_read_b128 v[212:215], v148 offset:19456
	ds_read_b128 v[216:219], v148 offset:20480
	ds_read_b128 v[220:223], v148 offset:21504
	ds_read_b128 v[224:227], v148 offset:22528
	ds_read_b128 v[234:237], v148 offset:23552
	global_load_lds_dwordx4 v[142:143], off
	v_lshl_add_u64 v[152:153], s[28:29], 0, v[130:131]
	s_mov_b32 m0, s39
	s_addc_u32 s53, s29, 0
	global_load_lds_dwordx4 v[152:153], off
	v_lshl_add_u64 v[194:195], s[52:53], 0, v[134:135]
	s_mov_b32 m0, s40
	v_lshl_add_u64 v[200:201], s[30:31], 0, v[132:133]
	global_load_lds_dwordx4 v[194:195], off
	v_lshl_add_u64 v[194:195], s[52:53], 0, v[130:131]
	s_mov_b32 m0, s41
	s_nop 0
	global_load_lds_dwordx4 v[194:195], off
	v_lshl_add_u64 v[194:195], s[30:31], 0, v[136:137]
	s_mov_b32 m0, s9
	s_nop 0
	global_load_lds_dwordx4 v[194:195], off
	s_mov_b32 m0, s13
	s_nop 0
	global_load_lds_dwordx4 v[200:201], off
	s_waitcnt vmcnt(8)
	s_waitcnt lgkmcnt(0)
	s_barrier
	s_waitcnt lgkmcnt(0)
	v_mfma_f32_16x16x32_bf16 v[62:65], v[156:159], v[190:193], v[62:65]
	v_mfma_f32_16x16x32_bf16 v[62:65], v[160:163], v[204:207], v[62:65]
	v_mfma_f32_16x16x32_bf16 v[58:61], v[164:167], v[190:193], v[58:61]
	v_mfma_f32_16x16x32_bf16 v[58:61], v[168:171], v[204:207], v[58:61]
	v_mfma_f32_16x16x32_bf16 v[54:57], v[156:159], v[208:211], v[54:57]
	v_mfma_f32_16x16x32_bf16 v[54:57], v[160:163], v[212:215], v[54:57]
	v_mfma_f32_16x16x32_bf16 v[46:49], v[164:167], v[208:211], v[46:49]
	v_mfma_f32_16x16x32_bf16 v[46:49], v[168:171], v[212:215], v[46:49]
	v_mfma_f32_16x16x32_bf16 v[38:41], v[156:159], v[216:219], v[38:41]
	v_mfma_f32_16x16x32_bf16 v[38:41], v[160:163], v[220:223], v[38:41]
	v_mfma_f32_16x16x32_bf16 v[30:33], v[164:167], v[216:219], v[30:33]
	v_mfma_f32_16x16x32_bf16 v[30:33], v[168:171], v[220:223], v[30:33]
	v_mfma_f32_16x16x32_bf16 v[22:25], v[156:159], v[224:227], v[22:25]
	v_mfma_f32_16x16x32_bf16 v[22:25], v[160:163], v[234:237], v[22:25]
	v_mfma_f32_16x16x32_bf16 v[14:17], v[164:167], v[224:227], v[14:17]
	v_mfma_f32_16x16x32_bf16 v[14:17], v[168:171], v[234:237], v[14:17]
	v_mfma_f32_16x16x32_bf16 v[50:53], v[172:175], v[190:193], v[50:53]
	v_mfma_f32_16x16x32_bf16 v[50:53], v[176:179], v[204:207], v[50:53]
	v_mfma_f32_16x16x32_bf16 v[42:45], v[180:183], v[190:193], v[42:45]
	v_mfma_f32_16x16x32_bf16 v[42:45], v[184:187], v[204:207], v[42:45]
	v_mfma_f32_16x16x32_bf16 v[34:37], v[172:175], v[208:211], v[34:37]
	v_mfma_f32_16x16x32_bf16 v[34:37], v[176:179], v[212:215], v[34:37]
	v_mfma_f32_16x16x32_bf16 v[26:29], v[180:183], v[208:211], v[26:29]
	v_mfma_f32_16x16x32_bf16 v[26:29], v[184:187], v[212:215], v[26:29]
	v_mfma_f32_16x16x32_bf16 v[18:21], v[172:175], v[216:219], v[18:21]
	v_mfma_f32_16x16x32_bf16 v[18:21], v[176:179], v[220:223], v[18:21]
	v_mfma_f32_16x16x32_bf16 v[10:13], v[180:183], v[216:219], v[10:13]
	v_mfma_f32_16x16x32_bf16 v[10:13], v[184:187], v[220:223], v[10:13]
	v_mfma_f32_16x16x32_bf16 v[6:9], v[172:175], v[224:227], v[6:9]
	v_mfma_f32_16x16x32_bf16 v[6:9], v[176:179], v[234:237], v[6:9]
	v_mfma_f32_16x16x32_bf16 v[2:5], v[180:183], v[224:227], v[2:5]
	v_mfma_f32_16x16x32_bf16 v[2:5], v[184:187], v[234:237], v[2:5]
	s_barrier
	ds_read_b128 v[156:159], v149
	ds_read_b128 v[160:163], v149 offset:1024
	ds_read_b128 v[164:167], v149 offset:2048
	ds_read_b128 v[168:171], v149 offset:3072
	ds_read_b128 v[172:175], v150
	ds_read_b128 v[176:179], v150 offset:1024
	ds_read_b128 v[180:183], v150 offset:2048
	ds_read_b128 v[184:187], v150 offset:3072
	s_add_u32 s30, s30, 0x100000
	s_addc_u32 s31, s31, 0
	s_mov_b32 m0, s14
	v_lshl_add_u64 v[238:239], s[30:31], 0, v[136:137]
	ds_read_b128 v[190:193], v148 offset:32768
	ds_read_b128 v[204:207], v148 offset:33792
	ds_read_b128 v[208:211], v148 offset:34816
	ds_read_b128 v[212:215], v148 offset:35840
	ds_read_b128 v[216:219], v148 offset:36864
	ds_read_b128 v[220:223], v148 offset:37888
	ds_read_b128 v[224:227], v148 offset:38912
	ds_read_b128 v[234:237], v148 offset:39936
	global_load_lds_dwordx4 v[238:239], off
	v_lshl_add_u64 v[238:239], s[30:31], 0, v[132:133]
	s_mov_b32 m0, s15
	s_nop 0
	global_load_lds_dwordx4 v[238:239], off
	s_waitcnt vmcnt(8)
	s_waitcnt lgkmcnt(0)
	s_barrier
	s_waitcnt lgkmcnt(0)
	v_mfma_f32_16x16x32_bf16 v[126:129], v[156:159], v[190:193], v[126:129]
	v_mfma_f32_16x16x32_bf16 v[126:129], v[160:163], v[204:207], v[126:129]
	v_mfma_f32_16x16x32_bf16 v[122:125], v[164:167], v[190:193], v[122:125]
	v_mfma_f32_16x16x32_bf16 v[122:125], v[168:171], v[204:207], v[122:125]
	v_mfma_f32_16x16x32_bf16 v[118:121], v[156:159], v[208:211], v[118:121]
	v_mfma_f32_16x16x32_bf16 v[118:121], v[160:163], v[212:215], v[118:121]
	v_mfma_f32_16x16x32_bf16 v[110:113], v[164:167], v[208:211], v[110:113]
	v_mfma_f32_16x16x32_bf16 v[110:113], v[168:171], v[212:215], v[110:113]
	v_mfma_f32_16x16x32_bf16 v[102:105], v[156:159], v[216:219], v[102:105]
	v_mfma_f32_16x16x32_bf16 v[102:105], v[160:163], v[220:223], v[102:105]
	v_mfma_f32_16x16x32_bf16 v[94:97], v[164:167], v[216:219], v[94:97]
	v_mfma_f32_16x16x32_bf16 v[94:97], v[168:171], v[220:223], v[94:97]
	v_mfma_f32_16x16x32_bf16 v[82:85], v[156:159], v[224:227], v[82:85]
	v_mfma_f32_16x16x32_bf16 v[82:85], v[160:163], v[234:237], v[82:85]
	v_mfma_f32_16x16x32_bf16 v[74:77], v[164:167], v[224:227], v[74:77]
	v_mfma_f32_16x16x32_bf16 v[74:77], v[168:171], v[234:237], v[74:77]
	v_mfma_f32_16x16x32_bf16 v[114:117], v[172:175], v[190:193], v[114:117]
	v_mfma_f32_16x16x32_bf16 v[114:117], v[176:179], v[204:207], v[114:117]
	v_mfma_f32_16x16x32_bf16 v[106:109], v[180:183], v[190:193], v[106:109]
	v_mfma_f32_16x16x32_bf16 v[106:109], v[184:187], v[204:207], v[106:109]
	v_mfma_f32_16x16x32_bf16 v[98:101], v[172:175], v[208:211], v[98:101]
	v_mfma_f32_16x16x32_bf16 v[98:101], v[176:179], v[212:215], v[98:101]
	v_mfma_f32_16x16x32_bf16 v[90:93], v[180:183], v[208:211], v[90:93]
	v_mfma_f32_16x16x32_bf16 v[90:93], v[184:187], v[212:215], v[90:93]
	v_mfma_f32_16x16x32_bf16 v[86:89], v[172:175], v[216:219], v[86:89]
	v_mfma_f32_16x16x32_bf16 v[86:89], v[176:179], v[220:223], v[86:89]
	v_mfma_f32_16x16x32_bf16 v[78:81], v[180:183], v[216:219], v[78:81]
	v_mfma_f32_16x16x32_bf16 v[78:81], v[184:187], v[220:223], v[78:81]
	v_mfma_f32_16x16x32_bf16 v[70:73], v[172:175], v[224:227], v[70:73]
	v_mfma_f32_16x16x32_bf16 v[70:73], v[176:179], v[234:237], v[70:73]
	v_mfma_f32_16x16x32_bf16 v[66:69], v[180:183], v[224:227], v[66:69]
	v_mfma_f32_16x16x32_bf16 v[66:69], v[184:187], v[234:237], v[66:69]
	s_barrier
	s_mov_b32 m0, s42
	v_lshl_add_u64 v[142:143], v[142:143], 0, s[4:5]
	s_add_u32 s28, s28, 0x20080
	ds_read_b128 v[190:193], v148 offset:49152
	ds_read_b128 v[204:207], v148 offset:50176
	ds_read_b128 v[208:211], v148 offset:51200
	ds_read_b128 v[212:215], v148 offset:52224
	ds_read_b128 v[216:219], v148 offset:53248
	ds_read_b128 v[220:223], v148 offset:54272
	ds_read_b128 v[224:227], v148 offset:55296
	ds_read_b128 v[234:237], v148 offset:56320
	global_load_lds_dwordx4 v[142:143], off
	v_lshl_add_u64 v[142:143], v[152:153], 0, s[4:5]
	s_mov_b32 m0, s43
	s_addc_u32 s29, s29, 0
	global_load_lds_dwordx4 v[142:143], off
	v_lshl_add_u64 v[142:143], s[28:29], 0, v[134:135]
	s_mov_b32 m0, s44
	s_nop 0
	global_load_lds_dwordx4 v[142:143], off
	v_lshl_add_u64 v[142:143], s[28:29], 0, v[130:131]
	s_mov_b32 m0, s45
	s_nop 0
	global_load_lds_dwordx4 v[142:143], off
	v_lshl_add_u64 v[142:143], v[194:195], 0, s[4:5]
	s_mov_b32 m0, s34
	s_nop 0
	global_load_lds_dwordx4 v[142:143], off
	v_lshl_add_u64 v[142:143], v[200:201], 0, s[4:5]
	s_mov_b32 m0, s35
	s_nop 0
	global_load_lds_dwordx4 v[142:143], off
	s_waitcnt vmcnt(8)
	s_waitcnt lgkmcnt(0)
	s_barrier
	s_waitcnt lgkmcnt(0)
	v_mfma_f32_16x16x32_bf16 v[62:65], v[156:159], v[190:193], v[62:65]
	v_mfma_f32_16x16x32_bf16 v[62:65], v[160:163], v[204:207], v[62:65]
	v_mfma_f32_16x16x32_bf16 v[58:61], v[164:167], v[190:193], v[58:61]
	v_mfma_f32_16x16x32_bf16 v[58:61], v[168:171], v[204:207], v[58:61]
	v_mfma_f32_16x16x32_bf16 v[54:57], v[156:159], v[208:211], v[54:57]
	v_mfma_f32_16x16x32_bf16 v[54:57], v[160:163], v[212:215], v[54:57]
	v_mfma_f32_16x16x32_bf16 v[46:49], v[164:167], v[208:211], v[46:49]
	v_mfma_f32_16x16x32_bf16 v[46:49], v[168:171], v[212:215], v[46:49]
	v_mfma_f32_16x16x32_bf16 v[38:41], v[156:159], v[216:219], v[38:41]
	v_mfma_f32_16x16x32_bf16 v[38:41], v[160:163], v[220:223], v[38:41]
	v_mfma_f32_16x16x32_bf16 v[30:33], v[164:167], v[216:219], v[30:33]
	v_mfma_f32_16x16x32_bf16 v[30:33], v[168:171], v[220:223], v[30:33]
	v_mfma_f32_16x16x32_bf16 v[22:25], v[156:159], v[224:227], v[22:25]
	v_mfma_f32_16x16x32_bf16 v[22:25], v[160:163], v[234:237], v[22:25]
	v_mfma_f32_16x16x32_bf16 v[14:17], v[164:167], v[224:227], v[14:17]
	v_mfma_f32_16x16x32_bf16 v[14:17], v[168:171], v[234:237], v[14:17]
	v_mfma_f32_16x16x32_bf16 v[50:53], v[172:175], v[190:193], v[50:53]
	v_mfma_f32_16x16x32_bf16 v[50:53], v[176:179], v[204:207], v[50:53]
	v_mfma_f32_16x16x32_bf16 v[42:45], v[180:183], v[190:193], v[42:45]
	v_mfma_f32_16x16x32_bf16 v[42:45], v[184:187], v[204:207], v[42:45]
	v_mfma_f32_16x16x32_bf16 v[34:37], v[172:175], v[208:211], v[34:37]
	v_mfma_f32_16x16x32_bf16 v[34:37], v[176:179], v[212:215], v[34:37]
	v_mfma_f32_16x16x32_bf16 v[26:29], v[180:183], v[208:211], v[26:29]
	v_mfma_f32_16x16x32_bf16 v[26:29], v[184:187], v[212:215], v[26:29]
	v_mfma_f32_16x16x32_bf16 v[18:21], v[172:175], v[216:219], v[18:21]
	v_mfma_f32_16x16x32_bf16 v[18:21], v[176:179], v[220:223], v[18:21]
	v_mfma_f32_16x16x32_bf16 v[10:13], v[180:183], v[216:219], v[10:13]
	v_mfma_f32_16x16x32_bf16 v[10:13], v[184:187], v[220:223], v[10:13]
	v_mfma_f32_16x16x32_bf16 v[6:9], v[172:175], v[224:227], v[6:9]
	v_mfma_f32_16x16x32_bf16 v[6:9], v[176:179], v[234:237], v[6:9]
	v_mfma_f32_16x16x32_bf16 v[2:5], v[180:183], v[224:227], v[2:5]
	v_mfma_f32_16x16x32_bf16 v[2:5], v[184:187], v[234:237], v[2:5]
	s_barrier
	s_add_i32 s50, s50, 2
	s_add_u32 s26, s26, 0x100
	s_addc_u32 s27, s27, 0
	s_add_u32 s23, s23, 0x100
	s_addc_u32 s49, s49, 0
	s_cmp_gt_u32 s50, 5
	s_cbranch_scc0 .LBB0_514
	s_and_b64 vcc, exec, s[6:7]
	s_cbranch_vccz .LBB0_517
	s_barrier

.LBB0_752:
	ds_read_b128 v[134:137], v227
	ds_read_b128 v[138:141], v227 offset:1024
	ds_read_b128 v[142:145], v227 offset:2048
	ds_read_b128 v[146:149], v227 offset:3072
	ds_read_b128 v[150:153], v233
	ds_read_b128 v[154:157], v233 offset:1024
	ds_read_b128 v[158:161], v233 offset:2048
	ds_read_b128 v[162:165], v233 offset:3072
	s_add_u32 s30, s29, s2
	s_addc_u32 s31, s33, s3
	s_add_u32 s30, s30, 0x200100
	s_addc_u32 s31, s31, 0
	s_add_u32 s77, s25, s2
	s_addc_u32 s78, s40, s3
	s_cmpk_eq_i32 s2, 0xf00
	s_cselect_b32 s35, s0, s31
	s_cselect_b32 s34, s1, s30
	s_cselect_b32 s31, s14, s78
	s_cselect_b32 s30, s15, s77
	s_mov_b32 m0, s66
	v_lshl_add_u64 v[242:243], v[130:131], 0, s[2:3]
	ds_read_b128 v[166:169], v226
	ds_read_b128 v[170:173], v226 offset:1024
	ds_read_b128 v[174:177], v226 offset:2048
	ds_read_b128 v[178:181], v226 offset:3072
	ds_read_b128 v[182:185], v226 offset:4096
	ds_read_b128 v[186:189], v226 offset:5120
	ds_read_b128 v[190:193], v226 offset:6144
	ds_read_b128 v[238:241], v226 offset:7168
	global_load_lds_dwordx4 v[242:243], off
	v_lshl_add_u64 v[242:243], v[132:133], 0, s[2:3]
	s_mov_b32 m0, s67
	s_nop 0
	global_load_lds_dwordx4 v[242:243], off
	s_waitcnt vmcnt(8)
	s_waitcnt lgkmcnt(0)
	s_barrier
	s_waitcnt lgkmcnt(0)
	v_mfma_f32_16x16x32_bf16 v[26:29], v[134:137], v[166:169], v[26:29]
	v_mfma_f32_16x16x32_bf16 v[26:29], v[138:141], v[170:173], v[26:29]
	v_mfma_f32_16x16x32_bf16 v[30:33], v[142:145], v[166:169], v[30:33]
	v_mfma_f32_16x16x32_bf16 v[30:33], v[146:149], v[170:173], v[30:33]
	v_mfma_f32_16x16x32_bf16 v[42:45], v[134:137], v[174:177], v[42:45]
	v_mfma_f32_16x16x32_bf16 v[42:45], v[138:141], v[178:181], v[42:45]
	v_mfma_f32_16x16x32_bf16 v[46:49], v[142:145], v[174:177], v[46:49]
	v_mfma_f32_16x16x32_bf16 v[46:49], v[146:149], v[178:181], v[46:49]
	v_mfma_f32_16x16x32_bf16 v[70:73], v[134:137], v[182:185], v[70:73]
	v_mfma_f32_16x16x32_bf16 v[70:73], v[138:141], v[186:189], v[70:73]
	v_mfma_f32_16x16x32_bf16 v[74:77], v[142:145], v[182:185], v[74:77]
	v_mfma_f32_16x16x32_bf16 v[74:77], v[146:149], v[186:189], v[74:77]
	v_mfma_f32_16x16x32_bf16 v[90:93], v[134:137], v[190:193], v[90:93]
	v_mfma_f32_16x16x32_bf16 v[90:93], v[138:141], v[238:241], v[90:93]
	v_mfma_f32_16x16x32_bf16 v[94:97], v[142:145], v[190:193], v[94:97]
	v_mfma_f32_16x16x32_bf16 v[94:97], v[146:149], v[238:241], v[94:97]
	v_mfma_f32_16x16x32_bf16 v[34:37], v[150:153], v[166:169], v[34:37]
	v_mfma_f32_16x16x32_bf16 v[34:37], v[154:157], v[170:173], v[34:37]
	v_mfma_f32_16x16x32_bf16 v[38:41], v[158:161], v[166:169], v[38:41]
	v_mfma_f32_16x16x32_bf16 v[38:41], v[162:165], v[170:173], v[38:41]
	v_mfma_f32_16x16x32_bf16 v[54:57], v[150:153], v[174:177], v[54:57]
	v_mfma_f32_16x16x32_bf16 v[54:57], v[154:157], v[178:181], v[54:57]
	v_mfma_f32_16x16x32_bf16 v[58:61], v[158:161], v[174:177], v[58:61]
	v_mfma_f32_16x16x32_bf16 v[58:61], v[162:165], v[178:181], v[58:61]
	v_mfma_f32_16x16x32_bf16 v[82:85], v[150:153], v[182:185], v[82:85]
	v_mfma_f32_16x16x32_bf16 v[82:85], v[154:157], v[186:189], v[82:85]
	v_mfma_f32_16x16x32_bf16 v[86:89], v[158:161], v[182:185], v[86:89]
	v_mfma_f32_16x16x32_bf16 v[86:89], v[162:165], v[186:189], v[86:89]
	v_mfma_f32_16x16x32_bf16 v[98:101], v[150:153], v[190:193], v[98:101]
	v_mfma_f32_16x16x32_bf16 v[98:101], v[154:157], v[238:241], v[98:101]
	v_mfma_f32_16x16x32_bf16 v[102:105], v[158:161], v[190:193], v[102:105]
	v_mfma_f32_16x16x32_bf16 v[102:105], v[162:165], v[238:241], v[102:105]
	s_barrier
	s_mov_b32 m0, s68
	v_lshl_add_u64 v[242:243], s[30:31], 0, v[202:203]
	s_add_u32 s78, s30, 0x80000
	ds_read_b128 v[166:169], v226 offset:16384
	ds_read_b128 v[170:173], v226 offset:17408
	ds_read_b128 v[174:177], v226 offset:18432
	ds_read_b128 v[178:181], v226 offset:19456
	ds_read_b128 v[182:185], v226 offset:20480
	ds_read_b128 v[186:189], v226 offset:21504
	ds_read_b128 v[190:193], v226 offset:22528
	ds_read_b128 v[238:241], v226 offset:23552
	global_load_lds_dwordx4 v[242:243], off
	v_lshl_add_u64 v[244:245], s[30:31], 0, v[206:207]
	s_mov_b32 m0, s69
	s_addc_u32 s79, s31, 0
	global_load_lds_dwordx4 v[244:245], off
	v_lshl_add_u64 v[246:247], s[78:79], 0, v[202:203]
	s_mov_b32 m0, s70
	v_lshl_add_u64 v[248:249], s[34:35], 0, v[204:205]
	global_load_lds_dwordx4 v[246:247], off
	v_lshl_add_u64 v[246:247], s[78:79], 0, v[206:207]
	s_mov_b32 m0, s71
	s_nop 0
	global_load_lds_dwordx4 v[246:247], off
	v_lshl_add_u64 v[246:247], s[34:35], 0, v[194:195]
	s_mov_b32 m0, s23
	s_nop 0
	global_load_lds_dwordx4 v[246:247], off
	s_mov_b32 m0, s42
	s_nop 0
	global_load_lds_dwordx4 v[248:249], off
	s_waitcnt vmcnt(8)
	s_waitcnt lgkmcnt(0)
	s_barrier
	s_waitcnt lgkmcnt(0)
	v_mfma_f32_16x16x32_bf16 v[106:109], v[134:137], v[166:169], v[106:109]
	v_mfma_f32_16x16x32_bf16 v[106:109], v[138:141], v[170:173], v[106:109]
	v_mfma_f32_16x16x32_bf16 v[110:113], v[142:145], v[166:169], v[110:113]
	v_mfma_f32_16x16x32_bf16 v[110:113], v[146:149], v[170:173], v[110:113]
	v_mfma_f32_16x16x32_bf16 v[118:121], v[134:137], v[174:177], v[118:121]
	v_mfma_f32_16x16x32_bf16 v[118:121], v[138:141], v[178:181], v[118:121]
	v_mfma_f32_16x16x32_bf16 v[126:129], v[142:145], v[174:177], v[126:129]
	v_mfma_f32_16x16x32_bf16 v[126:129], v[146:149], v[178:181], v[126:129]
	v_mfma_f32_16x16x32_bf16 v[50:53], v[134:137], v[182:185], v[50:53]
	v_mfma_f32_16x16x32_bf16 v[50:53], v[138:141], v[186:189], v[50:53]
	v_mfma_f32_16x16x32_bf16 v[62:65], v[142:145], v[182:185], v[62:65]
	v_mfma_f32_16x16x32_bf16 v[62:65], v[146:149], v[186:189], v[62:65]
	v_mfma_f32_16x16x32_bf16 v[10:13], v[134:137], v[190:193], v[10:13]
	v_mfma_f32_16x16x32_bf16 v[10:13], v[138:141], v[238:241], v[10:13]
	v_mfma_f32_16x16x32_bf16 v[14:17], v[142:145], v[190:193], v[14:17]
	v_mfma_f32_16x16x32_bf16 v[14:17], v[146:149], v[238:241], v[14:17]
	v_mfma_f32_16x16x32_bf16 v[114:117], v[150:153], v[166:169], v[114:117]
	v_mfma_f32_16x16x32_bf16 v[114:117], v[154:157], v[170:173], v[114:117]
	v_mfma_f32_16x16x32_bf16 v[122:125], v[158:161], v[166:169], v[122:125]
	v_mfma_f32_16x16x32_bf16 v[122:125], v[162:165], v[170:173], v[122:125]
	v_mfma_f32_16x16x32_bf16 v[66:69], v[150:153], v[174:177], v[66:69]
	v_mfma_f32_16x16x32_bf16 v[66:69], v[154:157], v[178:181], v[66:69]
	v_mfma_f32_16x16x32_bf16 v[78:81], v[158:161], v[174:177], v[78:81]
	v_mfma_f32_16x16x32_bf16 v[78:81], v[162:165], v[178:181], v[78:81]
	v_mfma_f32_16x16x32_bf16 v[18:21], v[150:153], v[182:185], v[18:21]
	v_mfma_f32_16x16x32_bf16 v[18:21], v[154:157], v[186:189], v[18:21]
	v_mfma_f32_16x16x32_bf16 v[22:25], v[158:161], v[182:185], v[22:25]
	v_mfma_f32_16x16x32_bf16 v[22:25], v[162:165], v[186:189], v[22:25]
	v_mfma_f32_16x16x32_bf16 v[2:5], v[150:153], v[190:193], v[2:5]
	v_mfma_f32_16x16x32_bf16 v[2:5], v[154:157], v[238:241], v[2:5]
	v_mfma_f32_16x16x32_bf16 v[6:9], v[158:161], v[190:193], v[6:9]
	v_mfma_f32_16x16x32_bf16 v[6:9], v[162:165], v[238:241], v[6:9]
	s_barrier
	ds_read_b128 v[134:137], v235
	ds_read_b128 v[138:141], v235 offset:1024
	ds_read_b128 v[142:145], v235 offset:2048
	ds_read_b128 v[146:149], v235 offset:3072
	ds_read_b128 v[150:153], v236
	ds_read_b128 v[154:157], v236 offset:1024
	ds_read_b128 v[158:161], v236 offset:2048
	ds_read_b128 v[162:165], v236 offset:3072
	s_add_u32 s34, s34, 0x80000
	s_addc_u32 s35, s35, 0
	s_mov_b32 m0, s43
	v_lshl_add_u64 v[250:251], s[34:35], 0, v[194:195]
	ds_read_b128 v[166:169], v226 offset:32768
	ds_read_b128 v[170:173], v226 offset:33792
	ds_read_b128 v[174:177], v226 offset:34816
	ds_read_b128 v[178:181], v226 offset:35840
	ds_read_b128 v[182:185], v226 offset:36864
	ds_read_b128 v[186:189], v226 offset:37888
	ds_read_b128 v[190:193], v226 offset:38912
	ds_read_b128 v[238:241], v226 offset:39936
	global_load_lds_dwordx4 v[250:251], off
	v_lshl_add_u64 v[250:251], s[34:35], 0, v[204:205]
	s_mov_b32 m0, s44
	s_nop 0
	global_load_lds_dwordx4 v[250:251], off
	s_waitcnt vmcnt(8)
	s_waitcnt lgkmcnt(0)
	s_barrier
	s_waitcnt lgkmcnt(0)
	v_mfma_f32_16x16x32_bf16 v[26:29], v[134:137], v[166:169], v[26:29]
	v_mfma_f32_16x16x32_bf16 v[26:29], v[138:141], v[170:173], v[26:29]
	v_mfma_f32_16x16x32_bf16 v[30:33], v[142:145], v[166:169], v[30:33]
	v_mfma_f32_16x16x32_bf16 v[30:33], v[146:149], v[170:173], v[30:33]
	v_mfma_f32_16x16x32_bf16 v[42:45], v[134:137], v[174:177], v[42:45]
	v_mfma_f32_16x16x32_bf16 v[42:45], v[138:141], v[178:181], v[42:45]
	v_mfma_f32_16x16x32_bf16 v[46:49], v[142:145], v[174:177], v[46:49]
	v_mfma_f32_16x16x32_bf16 v[46:49], v[146:149], v[178:181], v[46:49]
	v_mfma_f32_16x16x32_bf16 v[70:73], v[134:137], v[182:185], v[70:73]
	v_mfma_f32_16x16x32_bf16 v[70:73], v[138:141], v[186:189], v[70:73]
	v_mfma_f32_16x16x32_bf16 v[74:77], v[142:145], v[182:185], v[74:77]
	v_mfma_f32_16x16x32_bf16 v[74:77], v[146:149], v[186:189], v[74:77]
	v_mfma_f32_16x16x32_bf16 v[90:93], v[134:137], v[190:193], v[90:93]
	v_mfma_f32_16x16x32_bf16 v[90:93], v[138:141], v[238:241], v[90:93]
	v_mfma_f32_16x16x32_bf16 v[94:97], v[142:145], v[190:193], v[94:97]
	v_mfma_f32_16x16x32_bf16 v[94:97], v[146:149], v[238:241], v[94:97]
	v_mfma_f32_16x16x32_bf16 v[34:37], v[150:153], v[166:169], v[34:37]
	v_mfma_f32_16x16x32_bf16 v[34:37], v[154:157], v[170:173], v[34:37]
	v_mfma_f32_16x16x32_bf16 v[38:41], v[158:161], v[166:169], v[38:41]
	v_mfma_f32_16x16x32_bf16 v[38:41], v[162:165], v[170:173], v[38:41]
	v_mfma_f32_16x16x32_bf16 v[54:57], v[150:153], v[174:177], v[54:57]
	v_mfma_f32_16x16x32_bf16 v[54:57], v[154:157], v[178:181], v[54:57]
	v_mfma_f32_16x16x32_bf16 v[58:61], v[158:161], v[174:177], v[58:61]
	v_mfma_f32_16x16x32_bf16 v[58:61], v[162:165], v[178:181], v[58:61]
	v_mfma_f32_16x16x32_bf16 v[82:85], v[150:153], v[182:185], v[82:85]
	v_mfma_f32_16x16x32_bf16 v[82:85], v[154:157], v[186:189], v[82:85]
	v_mfma_f32_16x16x32_bf16 v[86:89], v[158:161], v[182:185], v[86:89]
	v_mfma_f32_16x16x32_bf16 v[86:89], v[162:165], v[186:189], v[86:89]
	v_mfma_f32_16x16x32_bf16 v[98:101], v[150:153], v[190:193], v[98:101]
	v_mfma_f32_16x16x32_bf16 v[98:101], v[154:157], v[238:241], v[98:101]
	v_mfma_f32_16x16x32_bf16 v[102:105], v[158:161], v[190:193], v[102:105]
	v_mfma_f32_16x16x32_bf16 v[102:105], v[162:165], v[238:241], v[102:105]
	s_barrier
	s_mov_b32 m0, s72
	v_lshl_add_u64 v[242:243], v[242:243], 0, s[6:7]
	s_add_u32 s30, s30, 0x80080
	ds_read_b128 v[166:169], v226 offset:49152
	ds_read_b128 v[170:173], v226 offset:50176
	ds_read_b128 v[174:177], v226 offset:51200
	ds_read_b128 v[178:181], v226 offset:52224
	ds_read_b128 v[182:185], v226 offset:53248
	ds_read_b128 v[186:189], v226 offset:54272
	ds_read_b128 v[190:193], v226 offset:55296
	ds_read_b128 v[238:241], v226 offset:56320
	global_load_lds_dwordx4 v[242:243], off
	v_lshl_add_u64 v[242:243], v[244:245], 0, s[6:7]
	s_mov_b32 m0, s73
	s_addc_u32 s31, s31, 0
	global_load_lds_dwordx4 v[242:243], off
	v_lshl_add_u64 v[242:243], s[30:31], 0, v[202:203]
	s_mov_b32 m0, s74
	s_nop 0
	global_load_lds_dwordx4 v[242:243], off
	v_lshl_add_u64 v[242:243], s[30:31], 0, v[206:207]
	s_mov_b32 m0, s75
	s_nop 0
	global_load_lds_dwordx4 v[242:243], off
	v_lshl_add_u64 v[242:243], v[246:247], 0, s[6:7]
	s_mov_b32 m0, s51
	s_nop 0
	global_load_lds_dwordx4 v[242:243], off
	v_lshl_add_u64 v[242:243], v[248:249], 0, s[6:7]
	s_mov_b32 m0, s53
	s_nop 0
	global_load_lds_dwordx4 v[242:243], off
	s_waitcnt vmcnt(8)
	s_waitcnt lgkmcnt(0)
	s_barrier
	s_waitcnt lgkmcnt(0)
	v_mfma_f32_16x16x32_bf16 v[106:109], v[134:137], v[166:169], v[106:109]
	v_mfma_f32_16x16x32_bf16 v[106:109], v[138:141], v[170:173], v[106:109]
	v_mfma_f32_16x16x32_bf16 v[110:113], v[142:145], v[166:169], v[110:113]
	v_mfma_f32_16x16x32_bf16 v[110:113], v[146:149], v[170:173], v[110:113]
	v_mfma_f32_16x16x32_bf16 v[118:121], v[134:137], v[174:177], v[118:121]
	v_mfma_f32_16x16x32_bf16 v[118:121], v[138:141], v[178:181], v[118:121]
	v_mfma_f32_16x16x32_bf16 v[126:129], v[142:145], v[174:177], v[126:129]
	v_mfma_f32_16x16x32_bf16 v[126:129], v[146:149], v[178:181], v[126:129]
	v_mfma_f32_16x16x32_bf16 v[50:53], v[134:137], v[182:185], v[50:53]
	v_mfma_f32_16x16x32_bf16 v[50:53], v[138:141], v[186:189], v[50:53]
	v_mfma_f32_16x16x32_bf16 v[62:65], v[142:145], v[182:185], v[62:65]
	v_mfma_f32_16x16x32_bf16 v[62:65], v[146:149], v[186:189], v[62:65]
	v_mfma_f32_16x16x32_bf16 v[10:13], v[134:137], v[190:193], v[10:13]
	v_mfma_f32_16x16x32_bf16 v[10:13], v[138:141], v[238:241], v[10:13]
	v_mfma_f32_16x16x32_bf16 v[14:17], v[142:145], v[190:193], v[14:17]
	v_mfma_f32_16x16x32_bf16 v[14:17], v[146:149], v[238:241], v[14:17]
	v_mfma_f32_16x16x32_bf16 v[114:117], v[150:153], v[166:169], v[114:117]
	v_mfma_f32_16x16x32_bf16 v[114:117], v[154:157], v[170:173], v[114:117]
	v_mfma_f32_16x16x32_bf16 v[122:125], v[158:161], v[166:169], v[122:125]
	v_mfma_f32_16x16x32_bf16 v[122:125], v[162:165], v[170:173], v[122:125]
	v_mfma_f32_16x16x32_bf16 v[66:69], v[150:153], v[174:177], v[66:69]
	v_mfma_f32_16x16x32_bf16 v[66:69], v[154:157], v[178:181], v[66:69]
	v_mfma_f32_16x16x32_bf16 v[78:81], v[158:161], v[174:177], v[78:81]
	v_mfma_f32_16x16x32_bf16 v[78:81], v[162:165], v[178:181], v[78:81]
	v_mfma_f32_16x16x32_bf16 v[18:21], v[150:153], v[182:185], v[18:21]
	v_mfma_f32_16x16x32_bf16 v[18:21], v[154:157], v[186:189], v[18:21]
	v_mfma_f32_16x16x32_bf16 v[22:25], v[158:161], v[182:185], v[22:25]
	v_mfma_f32_16x16x32_bf16 v[22:25], v[162:165], v[186:189], v[22:25]
	v_mfma_f32_16x16x32_bf16 v[2:5], v[150:153], v[190:193], v[2:5]
	v_mfma_f32_16x16x32_bf16 v[2:5], v[154:157], v[238:241], v[2:5]
	v_mfma_f32_16x16x32_bf16 v[6:9], v[158:161], v[190:193], v[6:9]
	v_mfma_f32_16x16x32_bf16 v[6:9], v[162:165], v[238:241], v[6:9]
	s_barrier
	s_add_i32 s41, s41, 2
	s_add_u32 s2, s2, 0x100
	s_addc_u32 s3, s3, 0
	s_cmp_gt_u32 s41, 29
	s_cbranch_scc0 .LBB0_752
	s_and_b64 vcc, exec, s[8:9]
	s_cbranch_vccz .LBB0_755
	s_barrier

.LBB0_817:
	ds_read_b128 v[130:133], v223
	ds_read_b128 v[134:137], v223 offset:1024
	ds_read_b128 v[138:141], v223 offset:2048
	ds_read_b128 v[142:145], v223 offset:3072
	ds_read_b128 v[146:149], v224
	ds_read_b128 v[150:153], v224 offset:1024
	ds_read_b128 v[154:157], v224 offset:2048
	ds_read_b128 v[158:161], v224 offset:3072
	s_add_u32 s6, s4, 0xfff00080
	s_addc_u32 s7, s5, -1
	s_cmp_eq_u32 s14, 60
	s_cselect_b32 s9, s19, s7
	s_cselect_b32 s8, s18, s6
	s_cselect_b32 s7, s79, s1
	s_cselect_b32 s6, s78, s0
	v_lshl_add_u64 v[194:195], s[4:5], 0, v[170:171]
	s_add_i32 m0, s35, 0xc000
	ds_read_b128 v[174:177], v225
	ds_read_b128 v[178:181], v225 offset:1024
	ds_read_b128 v[182:185], v225 offset:2048
	ds_read_b128 v[186:189], v225 offset:3072
	ds_read_b128 v[190:193], v225 offset:4096
	ds_read_b128 v[202:205], v225 offset:5120
	ds_read_b128 v[206:209], v225 offset:6144
	ds_read_b128 v[210:213], v225 offset:7168
	global_load_lds_dwordx4 v[194:195], off
	v_lshl_add_u64 v[194:195], s[4:5], 0, v[172:173]
	s_add_i32 m0, s35, 0xe000
	s_nop 0
	global_load_lds_dwordx4 v[194:195], off
	s_waitcnt vmcnt(8)
	s_waitcnt lgkmcnt(0)
	s_barrier
	s_waitcnt lgkmcnt(0)
	v_mfma_f32_16x16x32_bf16 v[14:17], v[130:133], v[174:177], v[14:17]
	v_mfma_f32_16x16x32_bf16 v[14:17], v[134:137], v[178:181], v[14:17]
	v_mfma_f32_16x16x32_bf16 v[10:13], v[138:141], v[174:177], v[10:13]
	v_mfma_f32_16x16x32_bf16 v[10:13], v[142:145], v[178:181], v[10:13]
	v_mfma_f32_16x16x32_bf16 v[34:37], v[130:133], v[182:185], v[34:37]
	v_mfma_f32_16x16x32_bf16 v[34:37], v[134:137], v[186:189], v[34:37]
	v_mfma_f32_16x16x32_bf16 v[26:29], v[138:141], v[182:185], v[26:29]
	v_mfma_f32_16x16x32_bf16 v[26:29], v[142:145], v[186:189], v[26:29]
	v_mfma_f32_16x16x32_bf16 v[46:49], v[130:133], v[190:193], v[46:49]
	v_mfma_f32_16x16x32_bf16 v[46:49], v[134:137], v[202:205], v[46:49]
	v_mfma_f32_16x16x32_bf16 v[42:45], v[138:141], v[190:193], v[42:45]
	v_mfma_f32_16x16x32_bf16 v[42:45], v[142:145], v[202:205], v[42:45]
	v_mfma_f32_16x16x32_bf16 v[62:65], v[130:133], v[206:209], v[62:65]
	v_mfma_f32_16x16x32_bf16 v[62:65], v[134:137], v[210:213], v[62:65]
	v_mfma_f32_16x16x32_bf16 v[58:61], v[138:141], v[206:209], v[58:61]
	v_mfma_f32_16x16x32_bf16 v[58:61], v[142:145], v[210:213], v[58:61]
	v_mfma_f32_16x16x32_bf16 v[6:9], v[146:149], v[174:177], v[6:9]
	v_mfma_f32_16x16x32_bf16 v[6:9], v[150:153], v[178:181], v[6:9]
	v_mfma_f32_16x16x32_bf16 v[2:5], v[154:157], v[174:177], v[2:5]
	v_mfma_f32_16x16x32_bf16 v[2:5], v[158:161], v[178:181], v[2:5]
	v_mfma_f32_16x16x32_bf16 v[22:25], v[146:149], v[182:185], v[22:25]
	v_mfma_f32_16x16x32_bf16 v[22:25], v[150:153], v[186:189], v[22:25]
	v_mfma_f32_16x16x32_bf16 v[18:21], v[154:157], v[182:185], v[18:21]
	v_mfma_f32_16x16x32_bf16 v[18:21], v[158:161], v[186:189], v[18:21]
	v_mfma_f32_16x16x32_bf16 v[38:41], v[146:149], v[190:193], v[38:41]
	v_mfma_f32_16x16x32_bf16 v[38:41], v[150:153], v[202:205], v[38:41]
	v_mfma_f32_16x16x32_bf16 v[30:33], v[154:157], v[190:193], v[30:33]
	v_mfma_f32_16x16x32_bf16 v[30:33], v[158:161], v[202:205], v[30:33]
	v_mfma_f32_16x16x32_bf16 v[54:57], v[146:149], v[206:209], v[54:57]
	v_mfma_f32_16x16x32_bf16 v[54:57], v[150:153], v[210:213], v[54:57]
	v_mfma_f32_16x16x32_bf16 v[50:53], v[154:157], v[206:209], v[50:53]
	v_mfma_f32_16x16x32_bf16 v[50:53], v[158:161], v[210:213], v[50:53]
	s_barrier
	s_add_i32 s15, s17, s33
	v_lshl_add_u64 v[194:195], s[6:7], 0, v[164:165]
	s_mov_b32 m0, s15
	ds_read_b128 v[174:177], v225 offset:16384
	ds_read_b128 v[178:181], v225 offset:17408
	ds_read_b128 v[182:185], v225 offset:18432
	ds_read_b128 v[186:189], v225 offset:19456
	ds_read_b128 v[190:193], v225 offset:20480
	ds_read_b128 v[202:205], v225 offset:21504
	ds_read_b128 v[206:209], v225 offset:22528
	ds_read_b128 v[210:213], v225 offset:23552
	global_load_lds_dwordx4 v[194:195], off
	s_add_i32 m0, s15, 0x2000
	s_add_u32 s44, s6, 0x100000
	v_lshl_add_u64 v[214:215], s[6:7], 0, v[168:169]
	s_addc_u32 s45, s7, 0
	s_add_i32 s15, s55, s33
	global_load_lds_dwordx4 v[214:215], off
	v_lshl_add_u64 v[216:217], s[44:45], 0, v[164:165]
	s_mov_b32 m0, s15
	v_lshl_add_u64 v[218:219], s[8:9], 0, v[166:167]
	global_load_lds_dwordx4 v[216:217], off
	v_lshl_add_u64 v[216:217], s[44:45], 0, v[168:169]
	s_add_i32 m0, s15, 0x2000
	s_nop 0
	global_load_lds_dwordx4 v[216:217], off
	v_lshl_add_u64 v[216:217], s[8:9], 0, v[162:163]
	s_mov_b32 m0, s35
	s_nop 0
	global_load_lds_dwordx4 v[216:217], off
	s_mov_b32 m0, s80
	s_nop 0
	global_load_lds_dwordx4 v[218:219], off
	s_waitcnt vmcnt(8)
	s_waitcnt lgkmcnt(0)
	s_barrier
	s_waitcnt lgkmcnt(0)
	v_mfma_f32_16x16x32_bf16 v[78:81], v[130:133], v[174:177], v[78:81]
	v_mfma_f32_16x16x32_bf16 v[78:81], v[134:137], v[178:181], v[78:81]
	v_mfma_f32_16x16x32_bf16 v[74:77], v[138:141], v[174:177], v[74:77]
	v_mfma_f32_16x16x32_bf16 v[74:77], v[142:145], v[178:181], v[74:77]
	v_mfma_f32_16x16x32_bf16 v[94:97], v[130:133], v[182:185], v[94:97]
	v_mfma_f32_16x16x32_bf16 v[94:97], v[134:137], v[186:189], v[94:97]
	v_mfma_f32_16x16x32_bf16 v[90:93], v[138:141], v[182:185], v[90:93]
	v_mfma_f32_16x16x32_bf16 v[90:93], v[142:145], v[186:189], v[90:93]
	v_mfma_f32_16x16x32_bf16 v[110:113], v[130:133], v[190:193], v[110:113]
	v_mfma_f32_16x16x32_bf16 v[110:113], v[134:137], v[202:205], v[110:113]
	v_mfma_f32_16x16x32_bf16 v[106:109], v[138:141], v[190:193], v[106:109]
	v_mfma_f32_16x16x32_bf16 v[106:109], v[142:145], v[202:205], v[106:109]
	v_mfma_f32_16x16x32_bf16 v[118:121], v[130:133], v[206:209], v[118:121]
	v_mfma_f32_16x16x32_bf16 v[118:121], v[134:137], v[210:213], v[118:121]
	v_mfma_f32_16x16x32_bf16 v[114:117], v[138:141], v[206:209], v[114:117]
	v_mfma_f32_16x16x32_bf16 v[114:117], v[142:145], v[210:213], v[114:117]
	v_mfma_f32_16x16x32_bf16 v[70:73], v[146:149], v[174:177], v[70:73]
	v_mfma_f32_16x16x32_bf16 v[70:73], v[150:153], v[178:181], v[70:73]
	v_mfma_f32_16x16x32_bf16 v[66:69], v[154:157], v[174:177], v[66:69]
	v_mfma_f32_16x16x32_bf16 v[66:69], v[158:161], v[178:181], v[66:69]
	v_mfma_f32_16x16x32_bf16 v[86:89], v[146:149], v[182:185], v[86:89]
	v_mfma_f32_16x16x32_bf16 v[86:89], v[150:153], v[186:189], v[86:89]
	v_mfma_f32_16x16x32_bf16 v[82:85], v[154:157], v[182:185], v[82:85]
	v_mfma_f32_16x16x32_bf16 v[82:85], v[158:161], v[186:189], v[82:85]
	v_mfma_f32_16x16x32_bf16 v[102:105], v[146:149], v[190:193], v[102:105]
	v_mfma_f32_16x16x32_bf16 v[102:105], v[150:153], v[202:205], v[102:105]
	v_mfma_f32_16x16x32_bf16 v[98:101], v[154:157], v[190:193], v[98:101]
	v_mfma_f32_16x16x32_bf16 v[98:101], v[158:161], v[202:205], v[98:101]
	v_mfma_f32_16x16x32_bf16 v[122:125], v[146:149], v[206:209], v[122:125]
	v_mfma_f32_16x16x32_bf16 v[122:125], v[150:153], v[210:213], v[122:125]
	v_mfma_f32_16x16x32_bf16 v[126:129], v[154:157], v[206:209], v[126:129]
	v_mfma_f32_16x16x32_bf16 v[126:129], v[158:161], v[210:213], v[126:129]
	s_barrier
	s_add_i32 s56, 0, 0x18000
	s_add_i32 s57, 0, 0x1c000
	v_add_u32_e32 v142, s56, v222
	v_add_u32_e32 v158, s57, v222
	ds_read_b128 v[130:133], v142
	ds_read_b128 v[134:137], v142 offset:1024
	ds_read_b128 v[138:141], v142 offset:2048
	ds_read_b128 v[142:145], v142 offset:3072
	ds_read_b128 v[146:149], v158
	ds_read_b128 v[150:153], v158 offset:1024
	ds_read_b128 v[154:157], v158 offset:2048
	ds_read_b128 v[158:161], v158 offset:3072
	s_add_u32 s8, s8, 0x100000
	s_addc_u32 s9, s9, 0
	s_mov_b32 m0, s59
	v_lshl_add_u64 v[238:239], s[8:9], 0, v[162:163]
	ds_read_b128 v[174:177], v225 offset:32768
	ds_read_b128 v[178:181], v225 offset:33792
	ds_read_b128 v[182:185], v225 offset:34816
	ds_read_b128 v[186:189], v225 offset:35840
	ds_read_b128 v[190:193], v225 offset:36864
	ds_read_b128 v[202:205], v225 offset:37888
	ds_read_b128 v[206:209], v225 offset:38912
	ds_read_b128 v[210:213], v225 offset:39936
	global_load_lds_dwordx4 v[238:239], off
	v_lshl_add_u64 v[238:239], s[8:9], 0, v[166:167]
	s_mov_b32 m0, s60
	s_nop 0
	global_load_lds_dwordx4 v[238:239], off
	s_waitcnt vmcnt(8)
	s_waitcnt lgkmcnt(0)
	s_barrier
	s_waitcnt lgkmcnt(0)
	v_mfma_f32_16x16x32_bf16 v[14:17], v[130:133], v[174:177], v[14:17]
	v_mfma_f32_16x16x32_bf16 v[14:17], v[134:137], v[178:181], v[14:17]
	v_mfma_f32_16x16x32_bf16 v[10:13], v[138:141], v[174:177], v[10:13]
	v_mfma_f32_16x16x32_bf16 v[10:13], v[142:145], v[178:181], v[10:13]
	v_mfma_f32_16x16x32_bf16 v[34:37], v[130:133], v[182:185], v[34:37]
	v_mfma_f32_16x16x32_bf16 v[34:37], v[134:137], v[186:189], v[34:37]
	v_mfma_f32_16x16x32_bf16 v[26:29], v[138:141], v[182:185], v[26:29]
	v_mfma_f32_16x16x32_bf16 v[26:29], v[142:145], v[186:189], v[26:29]
	v_mfma_f32_16x16x32_bf16 v[46:49], v[130:133], v[190:193], v[46:49]
	v_mfma_f32_16x16x32_bf16 v[46:49], v[134:137], v[202:205], v[46:49]
	v_mfma_f32_16x16x32_bf16 v[42:45], v[138:141], v[190:193], v[42:45]
	v_mfma_f32_16x16x32_bf16 v[42:45], v[142:145], v[202:205], v[42:45]
	v_mfma_f32_16x16x32_bf16 v[62:65], v[130:133], v[206:209], v[62:65]
	v_mfma_f32_16x16x32_bf16 v[62:65], v[134:137], v[210:213], v[62:65]
	v_mfma_f32_16x16x32_bf16 v[58:61], v[138:141], v[206:209], v[58:61]
	v_mfma_f32_16x16x32_bf16 v[58:61], v[142:145], v[210:213], v[58:61]
	v_mfma_f32_16x16x32_bf16 v[6:9], v[146:149], v[174:177], v[6:9]
	v_mfma_f32_16x16x32_bf16 v[6:9], v[150:153], v[178:181], v[6:9]
	v_mfma_f32_16x16x32_bf16 v[2:5], v[154:157], v[174:177], v[2:5]
	v_mfma_f32_16x16x32_bf16 v[2:5], v[158:161], v[178:181], v[2:5]
	v_mfma_f32_16x16x32_bf16 v[22:25], v[146:149], v[182:185], v[22:25]
	v_mfma_f32_16x16x32_bf16 v[22:25], v[150:153], v[186:189], v[22:25]
	v_mfma_f32_16x16x32_bf16 v[18:21], v[154:157], v[182:185], v[18:21]
	v_mfma_f32_16x16x32_bf16 v[18:21], v[158:161], v[186:189], v[18:21]
	v_mfma_f32_16x16x32_bf16 v[38:41], v[146:149], v[190:193], v[38:41]
	v_mfma_f32_16x16x32_bf16 v[38:41], v[150:153], v[202:205], v[38:41]
	v_mfma_f32_16x16x32_bf16 v[30:33], v[154:157], v[190:193], v[30:33]
	v_mfma_f32_16x16x32_bf16 v[30:33], v[158:161], v[202:205], v[30:33]
	v_mfma_f32_16x16x32_bf16 v[54:57], v[146:149], v[206:209], v[54:57]
	v_mfma_f32_16x16x32_bf16 v[54:57], v[150:153], v[210:213], v[54:57]
	v_mfma_f32_16x16x32_bf16 v[50:53], v[154:157], v[206:209], v[50:53]
	v_mfma_f32_16x16x32_bf16 v[50:53], v[158:161], v[210:213], v[50:53]
	s_barrier
	s_add_i32 s8, s56, s33
	v_lshl_add_u64 v[194:195], v[194:195], 0, s[26:27]
	s_mov_b32 m0, s8
	ds_read_b128 v[174:177], v225 offset:49152
	ds_read_b128 v[178:181], v225 offset:50176
	ds_read_b128 v[182:185], v225 offset:51200
	ds_read_b128 v[186:189], v225 offset:52224
	ds_read_b128 v[190:193], v225 offset:53248
	ds_read_b128 v[202:205], v225 offset:54272
	ds_read_b128 v[206:209], v225 offset:55296
	ds_read_b128 v[210:213], v225 offset:56320
	global_load_lds_dwordx4 v[194:195], off
	s_add_i32 m0, s8, 0x2000
	s_add_u32 s6, s6, 0x100080
	v_lshl_add_u64 v[194:195], v[214:215], 0, s[26:27]
	s_addc_u32 s7, s7, 0
	s_add_i32 s8, s57, s33
	global_load_lds_dwordx4 v[194:195], off
	v_lshl_add_u64 v[194:195], s[6:7], 0, v[164:165]
	s_mov_b32 m0, s8
	s_nop 0
	global_load_lds_dwordx4 v[194:195], off
	v_lshl_add_u64 v[194:195], s[6:7], 0, v[168:169]
	s_add_i32 m0, s8, 0x2000
	s_nop 0
	global_load_lds_dwordx4 v[194:195], off
	v_lshl_add_u64 v[194:195], v[216:217], 0, s[26:27]
	s_mov_b32 m0, s65
	s_nop 0
	global_load_lds_dwordx4 v[194:195], off
	v_lshl_add_u64 v[194:195], v[218:219], 0, s[26:27]
	s_mov_b32 m0, s66
	s_nop 0
	global_load_lds_dwordx4 v[194:195], off
	s_waitcnt vmcnt(8)
	s_waitcnt lgkmcnt(0)
	s_barrier
	s_waitcnt lgkmcnt(0)
	v_mfma_f32_16x16x32_bf16 v[78:81], v[130:133], v[174:177], v[78:81]
	v_mfma_f32_16x16x32_bf16 v[78:81], v[134:137], v[178:181], v[78:81]
	v_mfma_f32_16x16x32_bf16 v[74:77], v[138:141], v[174:177], v[74:77]
	v_mfma_f32_16x16x32_bf16 v[74:77], v[142:145], v[178:181], v[74:77]
	v_mfma_f32_16x16x32_bf16 v[94:97], v[130:133], v[182:185], v[94:97]
	v_mfma_f32_16x16x32_bf16 v[94:97], v[134:137], v[186:189], v[94:97]
	v_mfma_f32_16x16x32_bf16 v[90:93], v[138:141], v[182:185], v[90:93]
	v_mfma_f32_16x16x32_bf16 v[90:93], v[142:145], v[186:189], v[90:93]
	v_mfma_f32_16x16x32_bf16 v[110:113], v[130:133], v[190:193], v[110:113]
	v_mfma_f32_16x16x32_bf16 v[110:113], v[134:137], v[202:205], v[110:113]
	v_mfma_f32_16x16x32_bf16 v[106:109], v[138:141], v[190:193], v[106:109]
	v_mfma_f32_16x16x32_bf16 v[106:109], v[142:145], v[202:205], v[106:109]
	v_mfma_f32_16x16x32_bf16 v[118:121], v[130:133], v[206:209], v[118:121]
	v_mfma_f32_16x16x32_bf16 v[118:121], v[134:137], v[210:213], v[118:121]
	v_mfma_f32_16x16x32_bf16 v[114:117], v[138:141], v[206:209], v[114:117]
	v_mfma_f32_16x16x32_bf16 v[114:117], v[142:145], v[210:213], v[114:117]
	v_mfma_f32_16x16x32_bf16 v[70:73], v[146:149], v[174:177], v[70:73]
	v_mfma_f32_16x16x32_bf16 v[70:73], v[150:153], v[178:181], v[70:73]
	v_mfma_f32_16x16x32_bf16 v[66:69], v[154:157], v[174:177], v[66:69]
	v_mfma_f32_16x16x32_bf16 v[66:69], v[158:161], v[178:181], v[66:69]
	v_mfma_f32_16x16x32_bf16 v[86:89], v[146:149], v[182:185], v[86:89]
	v_mfma_f32_16x16x32_bf16 v[86:89], v[150:153], v[186:189], v[86:89]
	v_mfma_f32_16x16x32_bf16 v[82:85], v[154:157], v[182:185], v[82:85]
	v_mfma_f32_16x16x32_bf16 v[82:85], v[158:161], v[186:189], v[82:85]
	v_mfma_f32_16x16x32_bf16 v[102:105], v[146:149], v[190:193], v[102:105]
	v_mfma_f32_16x16x32_bf16 v[102:105], v[150:153], v[202:205], v[102:105]
	v_mfma_f32_16x16x32_bf16 v[98:101], v[154:157], v[190:193], v[98:101]
	v_mfma_f32_16x16x32_bf16 v[98:101], v[158:161], v[202:205], v[98:101]
	v_mfma_f32_16x16x32_bf16 v[122:125], v[146:149], v[206:209], v[122:125]
	v_mfma_f32_16x16x32_bf16 v[122:125], v[150:153], v[210:213], v[122:125]
	v_mfma_f32_16x16x32_bf16 v[126:129], v[154:157], v[206:209], v[126:129]
	v_mfma_f32_16x16x32_bf16 v[126:129], v[158:161], v[210:213], v[126:129]
	s_barrier
	s_add_i32 s14, s14, 2
	s_add_u32 s4, s4, 0x100
	s_addc_u32 s5, s5, 0
	s_add_u32 s0, s0, 0x100
	s_addc_u32 s1, s1, 0
	s_cmp_gt_u32 s14, 61
	s_cbranch_scc0 .LBB0_817
	s_and_b64 vcc, exec, s[28:29]
	s_cbranch_vccz .LBB0_820
	s_barrier

.LBB0_1058:
	ds_read_b128 v[128:131], v194
	ds_read_b128 v[132:135], v194 offset:1024
	ds_read_b128 v[136:139], v194 offset:2048
	ds_read_b128 v[140:143], v194 offset:3072
	ds_read_b128 v[144:147], v195
	ds_read_b128 v[148:151], v195 offset:1024
	ds_read_b128 v[152:155], v195 offset:2048
	ds_read_b128 v[156:159], v195 offset:3072
	s_add_u32 s2, s0, 0x100
	s_addc_u32 s3, s1, 0
	s_cmpk_eq_i32 s39, 0xa8
	s_cselect_b32 s37, s31, s3
	s_cselect_b32 s36, s30, s2
	s_cselect_b32 s5, s7, s38
	s_cselect_b32 s4, s6, s29
	v_lshl_add_u64 v[188:189], s[0:1], 0, v[168:169]
	s_add_i32 m0, s27, 0xc000
	ds_read_b128 v[172:175], v196
	ds_read_b128 v[176:179], v196 offset:1024
	ds_read_b128 v[180:183], v196 offset:2048
	ds_read_b128 v[184:187], v196 offset:3072
	ds_read_b128 v[200:203], v196 offset:4096
	ds_read_b128 v[204:207], v196 offset:5120
	ds_read_b128 v[208:211], v196 offset:6144
	ds_read_b128 v[212:215], v196 offset:7168
	global_load_lds_dwordx4 v[188:189], off
	v_lshl_add_u64 v[188:189], s[0:1], 0, v[170:171]
	s_add_i32 m0, s27, 0xe000
	s_nop 0
	global_load_lds_dwordx4 v[188:189], off
	s_waitcnt vmcnt(8)
	s_waitcnt lgkmcnt(0)
	s_barrier
	s_waitcnt lgkmcnt(0)
	v_mfma_f32_16x16x32_bf16 v[12:15], v[128:131], v[172:175], v[12:15]
	v_mfma_f32_16x16x32_bf16 v[12:15], v[132:135], v[176:179], v[12:15]
	v_mfma_f32_16x16x32_bf16 v[8:11], v[136:139], v[172:175], v[8:11]
	v_mfma_f32_16x16x32_bf16 v[8:11], v[140:143], v[176:179], v[8:11]
	v_mfma_f32_16x16x32_bf16 v[36:39], v[128:131], v[180:183], v[36:39]
	v_mfma_f32_16x16x32_bf16 v[36:39], v[132:135], v[184:187], v[36:39]
	v_mfma_f32_16x16x32_bf16 v[32:35], v[136:139], v[180:183], v[32:35]
	v_mfma_f32_16x16x32_bf16 v[32:35], v[140:143], v[184:187], v[32:35]
	v_mfma_f32_16x16x32_bf16 v[44:47], v[128:131], v[200:203], v[44:47]
	v_mfma_f32_16x16x32_bf16 v[44:47], v[132:135], v[204:207], v[44:47]
	v_mfma_f32_16x16x32_bf16 v[40:43], v[136:139], v[200:203], v[40:43]
	v_mfma_f32_16x16x32_bf16 v[40:43], v[140:143], v[204:207], v[40:43]
	v_mfma_f32_16x16x32_bf16 v[64:67], v[128:131], v[208:211], v[64:67]
	v_mfma_f32_16x16x32_bf16 v[64:67], v[132:135], v[212:215], v[64:67]
	v_mfma_f32_16x16x32_bf16 v[56:59], v[136:139], v[208:211], v[56:59]
	v_mfma_f32_16x16x32_bf16 v[56:59], v[140:143], v[212:215], v[56:59]
	v_mfma_f32_16x16x32_bf16 v[4:7], v[144:147], v[172:175], v[4:7]
	v_mfma_f32_16x16x32_bf16 v[4:7], v[148:151], v[176:179], v[4:7]
	v_mfma_f32_16x16x32_bf16 v[0:3], v[152:155], v[172:175], v[0:3]
	v_mfma_f32_16x16x32_bf16 v[0:3], v[156:159], v[176:179], v[0:3]
	v_mfma_f32_16x16x32_bf16 v[24:27], v[144:147], v[180:183], v[24:27]
	v_mfma_f32_16x16x32_bf16 v[24:27], v[148:151], v[184:187], v[24:27]
	v_mfma_f32_16x16x32_bf16 v[16:19], v[152:155], v[180:183], v[16:19]
	v_mfma_f32_16x16x32_bf16 v[16:19], v[156:159], v[184:187], v[16:19]
	v_mfma_f32_16x16x32_bf16 v[28:31], v[144:147], v[200:203], v[28:31]
	v_mfma_f32_16x16x32_bf16 v[28:31], v[148:151], v[204:207], v[28:31]
	v_mfma_f32_16x16x32_bf16 v[20:23], v[152:155], v[200:203], v[20:23]
	v_mfma_f32_16x16x32_bf16 v[20:23], v[156:159], v[204:207], v[20:23]
	v_mfma_f32_16x16x32_bf16 v[52:55], v[144:147], v[208:211], v[52:55]
	v_mfma_f32_16x16x32_bf16 v[52:55], v[148:151], v[212:215], v[52:55]
	v_mfma_f32_16x16x32_bf16 v[48:51], v[152:155], v[208:211], v[48:51]
	v_mfma_f32_16x16x32_bf16 v[48:51], v[156:159], v[212:215], v[48:51]
	s_barrier
	s_add_i32 s0, s17, s25
	v_lshl_add_u64 v[188:189], s[4:5], 0, v[162:163]
	s_mov_b32 m0, s0
	ds_read_b128 v[172:175], v196 offset:16384
	ds_read_b128 v[176:179], v196 offset:17408
	ds_read_b128 v[180:183], v196 offset:18432
	ds_read_b128 v[184:187], v196 offset:19456
	ds_read_b128 v[200:203], v196 offset:20480
	ds_read_b128 v[204:207], v196 offset:21504
	ds_read_b128 v[208:211], v196 offset:22528
	ds_read_b128 v[212:215], v196 offset:23552
	global_load_lds_dwordx4 v[188:189], off
	s_add_i32 m0, s0, 0x2000
	s_add_u32 s0, s4, 0x2b0000
	v_lshl_add_u64 v[216:217], s[4:5], 0, v[166:167]
	s_addc_u32 s1, s5, 0
	s_add_i32 s40, s55, s25
	global_load_lds_dwordx4 v[216:217], off
	v_lshl_add_u64 v[220:221], s[0:1], 0, v[162:163]
	s_mov_b32 m0, s40
	v_lshl_add_u64 v[222:223], s[36:37], 0, v[164:165]
	global_load_lds_dwordx4 v[220:221], off
	v_lshl_add_u64 v[220:221], s[0:1], 0, v[166:167]
	s_add_i32 m0, s40, 0x2000
	s_nop 0
	global_load_lds_dwordx4 v[220:221], off
	v_lshl_add_u64 v[220:221], s[36:37], 0, v[160:161]
	s_mov_b32 m0, s27
	s_nop 0
	global_load_lds_dwordx4 v[220:221], off
	s_mov_b32 m0, s33
	s_nop 0
	global_load_lds_dwordx4 v[222:223], off
	s_waitcnt vmcnt(8)
	s_waitcnt lgkmcnt(0)
	s_barrier
	s_waitcnt lgkmcnt(0)
	v_mfma_f32_16x16x32_bf16 v[76:79], v[128:131], v[172:175], v[76:79]
	v_mfma_f32_16x16x32_bf16 v[76:79], v[132:135], v[176:179], v[76:79]
	v_mfma_f32_16x16x32_bf16 v[72:75], v[136:139], v[172:175], v[72:75]
	v_mfma_f32_16x16x32_bf16 v[72:75], v[140:143], v[176:179], v[72:75]
	v_mfma_f32_16x16x32_bf16 v[92:95], v[128:131], v[180:183], v[92:95]
	v_mfma_f32_16x16x32_bf16 v[92:95], v[132:135], v[184:187], v[92:95]
	v_mfma_f32_16x16x32_bf16 v[88:91], v[136:139], v[180:183], v[88:91]
	v_mfma_f32_16x16x32_bf16 v[88:91], v[140:143], v[184:187], v[88:91]
	v_mfma_f32_16x16x32_bf16 v[108:111], v[128:131], v[200:203], v[108:111]
	v_mfma_f32_16x16x32_bf16 v[108:111], v[132:135], v[204:207], v[108:111]
	v_mfma_f32_16x16x32_bf16 v[104:107], v[136:139], v[200:203], v[104:107]
	v_mfma_f32_16x16x32_bf16 v[104:107], v[140:143], v[204:207], v[104:107]
	v_mfma_f32_16x16x32_bf16 v[124:127], v[128:131], v[208:211], v[124:127]
	v_mfma_f32_16x16x32_bf16 v[124:127], v[132:135], v[212:215], v[124:127]
	v_mfma_f32_16x16x32_bf16 v[120:123], v[136:139], v[208:211], v[120:123]
	v_mfma_f32_16x16x32_bf16 v[120:123], v[140:143], v[212:215], v[120:123]
	v_mfma_f32_16x16x32_bf16 v[68:71], v[144:147], v[172:175], v[68:71]
	v_mfma_f32_16x16x32_bf16 v[68:71], v[148:151], v[176:179], v[68:71]
	v_mfma_f32_16x16x32_bf16 v[60:63], v[152:155], v[172:175], v[60:63]
	v_mfma_f32_16x16x32_bf16 v[60:63], v[156:159], v[176:179], v[60:63]
	v_mfma_f32_16x16x32_bf16 v[84:87], v[144:147], v[180:183], v[84:87]
	v_mfma_f32_16x16x32_bf16 v[84:87], v[148:151], v[184:187], v[84:87]
	v_mfma_f32_16x16x32_bf16 v[80:83], v[152:155], v[180:183], v[80:83]
	v_mfma_f32_16x16x32_bf16 v[80:83], v[156:159], v[184:187], v[80:83]
	v_mfma_f32_16x16x32_bf16 v[100:103], v[144:147], v[200:203], v[100:103]
	v_mfma_f32_16x16x32_bf16 v[100:103], v[148:151], v[204:207], v[100:103]
	v_mfma_f32_16x16x32_bf16 v[96:99], v[152:155], v[200:203], v[96:99]
	v_mfma_f32_16x16x32_bf16 v[96:99], v[156:159], v[204:207], v[96:99]
	v_mfma_f32_16x16x32_bf16 v[116:119], v[144:147], v[208:211], v[116:119]
	v_mfma_f32_16x16x32_bf16 v[116:119], v[148:151], v[212:215], v[116:119]
	v_mfma_f32_16x16x32_bf16 v[112:115], v[152:155], v[208:211], v[112:115]
	v_mfma_f32_16x16x32_bf16 v[112:115], v[156:159], v[212:215], v[112:115]
	s_barrier
	v_add_u32_e32 v140, s56, v193
	v_add_u32_e32 v156, s57, v193
	ds_read_b128 v[128:131], v140
	ds_read_b128 v[132:135], v140 offset:1024
	ds_read_b128 v[136:139], v140 offset:2048
	ds_read_b128 v[140:143], v140 offset:3072
	ds_read_b128 v[144:147], v156
	ds_read_b128 v[148:151], v156 offset:1024
	ds_read_b128 v[152:155], v156 offset:2048
	ds_read_b128 v[156:159], v156 offset:3072
	s_add_u32 s0, s36, 0x2b0000
	s_addc_u32 s1, s37, 0
	s_mov_b32 m0, s46
	v_lshl_add_u64 v[224:225], s[0:1], 0, v[160:161]
	ds_read_b128 v[172:175], v196 offset:32768
	ds_read_b128 v[176:179], v196 offset:33792
	ds_read_b128 v[180:183], v196 offset:34816
	ds_read_b128 v[184:187], v196 offset:35840
	ds_read_b128 v[200:203], v196 offset:36864
	ds_read_b128 v[204:207], v196 offset:37888
	ds_read_b128 v[208:211], v196 offset:38912
	ds_read_b128 v[212:215], v196 offset:39936
	global_load_lds_dwordx4 v[224:225], off
	v_lshl_add_u64 v[224:225], s[0:1], 0, v[164:165]
	s_mov_b32 m0, s47
	s_nop 0
	global_load_lds_dwordx4 v[224:225], off
	s_waitcnt vmcnt(8)
	s_waitcnt lgkmcnt(0)
	s_barrier
	s_waitcnt lgkmcnt(0)
	v_mfma_f32_16x16x32_bf16 v[12:15], v[128:131], v[172:175], v[12:15]
	v_mfma_f32_16x16x32_bf16 v[12:15], v[132:135], v[176:179], v[12:15]
	v_mfma_f32_16x16x32_bf16 v[8:11], v[136:139], v[172:175], v[8:11]
	v_mfma_f32_16x16x32_bf16 v[8:11], v[140:143], v[176:179], v[8:11]
	v_mfma_f32_16x16x32_bf16 v[36:39], v[128:131], v[180:183], v[36:39]
	v_mfma_f32_16x16x32_bf16 v[36:39], v[132:135], v[184:187], v[36:39]
	v_mfma_f32_16x16x32_bf16 v[32:35], v[136:139], v[180:183], v[32:35]
	v_mfma_f32_16x16x32_bf16 v[32:35], v[140:143], v[184:187], v[32:35]
	v_mfma_f32_16x16x32_bf16 v[44:47], v[128:131], v[200:203], v[44:47]
	v_mfma_f32_16x16x32_bf16 v[44:47], v[132:135], v[204:207], v[44:47]
	v_mfma_f32_16x16x32_bf16 v[40:43], v[136:139], v[200:203], v[40:43]
	v_mfma_f32_16x16x32_bf16 v[40:43], v[140:143], v[204:207], v[40:43]
	v_mfma_f32_16x16x32_bf16 v[64:67], v[128:131], v[208:211], v[64:67]
	v_mfma_f32_16x16x32_bf16 v[64:67], v[132:135], v[212:215], v[64:67]
	v_mfma_f32_16x16x32_bf16 v[56:59], v[136:139], v[208:211], v[56:59]
	v_mfma_f32_16x16x32_bf16 v[56:59], v[140:143], v[212:215], v[56:59]
	v_mfma_f32_16x16x32_bf16 v[4:7], v[144:147], v[172:175], v[4:7]
	v_mfma_f32_16x16x32_bf16 v[4:7], v[148:151], v[176:179], v[4:7]
	v_mfma_f32_16x16x32_bf16 v[0:3], v[152:155], v[172:175], v[0:3]
	v_mfma_f32_16x16x32_bf16 v[0:3], v[156:159], v[176:179], v[0:3]
	v_mfma_f32_16x16x32_bf16 v[24:27], v[144:147], v[180:183], v[24:27]
	v_mfma_f32_16x16x32_bf16 v[24:27], v[148:151], v[184:187], v[24:27]
	v_mfma_f32_16x16x32_bf16 v[16:19], v[152:155], v[180:183], v[16:19]
	v_mfma_f32_16x16x32_bf16 v[16:19], v[156:159], v[184:187], v[16:19]
	v_mfma_f32_16x16x32_bf16 v[28:31], v[144:147], v[200:203], v[28:31]
	v_mfma_f32_16x16x32_bf16 v[28:31], v[148:151], v[204:207], v[28:31]
	v_mfma_f32_16x16x32_bf16 v[20:23], v[152:155], v[200:203], v[20:23]
	v_mfma_f32_16x16x32_bf16 v[20:23], v[156:159], v[204:207], v[20:23]
	v_mfma_f32_16x16x32_bf16 v[52:55], v[144:147], v[208:211], v[52:55]
	v_mfma_f32_16x16x32_bf16 v[52:55], v[148:151], v[212:215], v[52:55]
	v_mfma_f32_16x16x32_bf16 v[48:51], v[152:155], v[208:211], v[48:51]
	v_mfma_f32_16x16x32_bf16 v[48:51], v[156:159], v[212:215], v[48:51]
	s_barrier
	s_add_i32 s0, s56, s25
	v_lshl_add_u64 v[188:189], v[188:189], 0, s[18:19]
	s_mov_b32 m0, s0
	ds_read_b128 v[172:175], v196 offset:49152
	ds_read_b128 v[176:179], v196 offset:50176
	ds_read_b128 v[180:183], v196 offset:51200
	ds_read_b128 v[184:187], v196 offset:52224
	ds_read_b128 v[200:203], v196 offset:53248
	ds_read_b128 v[204:207], v196 offset:54272
	ds_read_b128 v[208:211], v196 offset:55296
	ds_read_b128 v[212:215], v196 offset:56320
	global_load_lds_dwordx4 v[188:189], off
	s_add_i32 m0, s0, 0x2000
	s_add_u32 s0, s4, 0x2b0080
	v_lshl_add_u64 v[188:189], v[216:217], 0, s[18:19]
	s_addc_u32 s1, s5, 0
	s_add_i32 s4, s57, s25
	global_load_lds_dwordx4 v[188:189], off
	v_lshl_add_u64 v[188:189], s[0:1], 0, v[162:163]
	s_mov_b32 m0, s4
	s_nop 0
	global_load_lds_dwordx4 v[188:189], off
	v_lshl_add_u64 v[188:189], s[0:1], 0, v[166:167]
	s_add_i32 m0, s4, 0x2000
	s_nop 0
	global_load_lds_dwordx4 v[188:189], off
	v_lshl_add_u64 v[188:189], v[220:221], 0, s[18:19]
	s_mov_b32 m0, s52
	s_nop 0
	global_load_lds_dwordx4 v[188:189], off
	v_lshl_add_u64 v[188:189], v[222:223], 0, s[18:19]
	s_mov_b32 m0, s53
	s_nop 0
	global_load_lds_dwordx4 v[188:189], off
	s_waitcnt vmcnt(8)
	s_waitcnt lgkmcnt(0)
	s_barrier
	s_waitcnt lgkmcnt(0)
	v_mfma_f32_16x16x32_bf16 v[76:79], v[128:131], v[172:175], v[76:79]
	v_mfma_f32_16x16x32_bf16 v[76:79], v[132:135], v[176:179], v[76:79]
	v_mfma_f32_16x16x32_bf16 v[72:75], v[136:139], v[172:175], v[72:75]
	v_mfma_f32_16x16x32_bf16 v[72:75], v[140:143], v[176:179], v[72:75]
	v_mfma_f32_16x16x32_bf16 v[92:95], v[128:131], v[180:183], v[92:95]
	v_mfma_f32_16x16x32_bf16 v[92:95], v[132:135], v[184:187], v[92:95]
	v_mfma_f32_16x16x32_bf16 v[88:91], v[136:139], v[180:183], v[88:91]
	v_mfma_f32_16x16x32_bf16 v[88:91], v[140:143], v[184:187], v[88:91]
	v_mfma_f32_16x16x32_bf16 v[108:111], v[128:131], v[200:203], v[108:111]
	v_mfma_f32_16x16x32_bf16 v[108:111], v[132:135], v[204:207], v[108:111]
	v_mfma_f32_16x16x32_bf16 v[104:107], v[136:139], v[200:203], v[104:107]
	v_mfma_f32_16x16x32_bf16 v[104:107], v[140:143], v[204:207], v[104:107]
	v_mfma_f32_16x16x32_bf16 v[124:127], v[128:131], v[208:211], v[124:127]
	v_mfma_f32_16x16x32_bf16 v[124:127], v[132:135], v[212:215], v[124:127]
	v_mfma_f32_16x16x32_bf16 v[120:123], v[136:139], v[208:211], v[120:123]
	v_mfma_f32_16x16x32_bf16 v[120:123], v[140:143], v[212:215], v[120:123]
	v_mfma_f32_16x16x32_bf16 v[68:71], v[144:147], v[172:175], v[68:71]
	v_mfma_f32_16x16x32_bf16 v[68:71], v[148:151], v[176:179], v[68:71]
	v_mfma_f32_16x16x32_bf16 v[60:63], v[152:155], v[172:175], v[60:63]
	v_mfma_f32_16x16x32_bf16 v[60:63], v[156:159], v[176:179], v[60:63]
	v_mfma_f32_16x16x32_bf16 v[84:87], v[144:147], v[180:183], v[84:87]
	v_mfma_f32_16x16x32_bf16 v[84:87], v[148:151], v[184:187], v[84:87]
	v_mfma_f32_16x16x32_bf16 v[80:83], v[152:155], v[180:183], v[80:83]
	v_mfma_f32_16x16x32_bf16 v[80:83], v[156:159], v[184:187], v[80:83]
	v_mfma_f32_16x16x32_bf16 v[100:103], v[144:147], v[200:203], v[100:103]
	v_mfma_f32_16x16x32_bf16 v[100:103], v[148:151], v[204:207], v[100:103]
	v_mfma_f32_16x16x32_bf16 v[96:99], v[152:155], v[200:203], v[96:99]
	v_mfma_f32_16x16x32_bf16 v[96:99], v[156:159], v[204:207], v[96:99]
	v_mfma_f32_16x16x32_bf16 v[116:119], v[144:147], v[208:211], v[116:119]
	v_mfma_f32_16x16x32_bf16 v[116:119], v[148:151], v[212:215], v[116:119]
	v_mfma_f32_16x16x32_bf16 v[112:115], v[152:155], v[208:211], v[112:115]
	v_mfma_f32_16x16x32_bf16 v[112:115], v[156:159], v[212:215], v[112:115]
	s_barrier
	s_add_i32 s39, s39, 2
	s_add_u32 s29, s29, 0x100
	s_addc_u32 s38, s38, 0
	s_cmpk_gt_u32 s39, 0xa9
	s_mov_b64 s[0:1], s[2:3]
	s_cbranch_scc0 .LBB0_1058
	s_and_b64 vcc, exec, s[20:21]
	s_cbranch_vccz .LBB0_1061
	s_barrier
